# nt2 + nt hint on the A8 quantisation row loads, V-repack loads and rmsnorm x-row loads (phase 0, P10)
# baseline (speedup 1.0000x reference)
; __device__ __forceinline__ unsigned cvt_pk_bf16(float lo, float hi) { unsigned r; asm volatile("v_cvt_pk_bf16_f32 %0, %1, %2" : "=v"(r) : "v"(lo), "v"(hi)); return r; }
; __device__ __forceinline__ void rms_row_to_bf16(const float* xrow, const float* g, bf16_t* orow, int lane, unsigned char* o8row = nullptr) {
;     const f32x4* xr = (const f32x4*)xrow + lane; const f32x4* gr = (const f32x4*)g + lane;
;     f32x4 v[16]; float s = 0.f;
; #pragma unroll
;     for (int j = 0; j < 16; ++j) { v[j] = xr[64 * j]; s += (v[j].x * v[j].x + v[j].y * v[j].y) + (v[j].z * v[j].z + v[j].w * v[j].w); }
;     const float rstd = 1.0f / sqrtf(wave_sum(s) * (1.f / D) + EPS);
;     u32x2* o8 = (u32x2*)orow + lane;
; #pragma unroll
;     for (int j = 0; j < 16; ++j) { const f32x4 gg = gr[64 * j]; const f32x4 y = v[j] * rstd * gg;
;         if (orow) { u32x2 w; w.x = cvt_pk_bf16(y.x, y.y); w.y = cvt_pk_bf16(y.z, y.w); o8[64 * j] = w; }
;         if (o8row) ((unsigned*)o8row)[lane + 64 * j] = pk4_i8(y.x, y.y, y.z, y.w, XN_QS); }
; }
.LBB0_89:
	v_add_co_u32_e64 v84, s[4:5], s2, v78
	global_load_dwordx4 v[12:15], v[78:79], off offset:-3072 nt
	global_load_dwordx4 v[8:11], v[78:79], off offset:-2048 nt
	global_load_dwordx4 v[4:7], v[78:79], off offset:-1024 nt
	v_addc_co_u32_e64 v85, s[4:5], -1, v79, s[4:5]
	v_add_co_u32_e32 v104, vcc, 0xffffd000, v78
	v_add_co_u32_e64 v86, s[4:5], s3, v78
	s_nop 0
	v_addc_co_u32_e32 v105, vcc, -1, v79, vcc
	v_addc_co_u32_e64 v87, s[4:5], -1, v79, s[4:5]
	global_load_dwordx4 v[0:3], v[78:79], off nt
	global_load_dwordx4 v[20:23], v[52:53], off
	global_load_dwordx4 v[48:51], v[84:85], off offset:-3072 nt
	global_load_dwordx4 v[44:47], v[84:85], off offset:-2048 nt
	global_load_dwordx4 v[40:43], v[84:85], off offset:-1024 nt
	global_load_dwordx4 v[36:39], v[84:85], off nt
	global_load_dwordx4 v[32:35], v[86:87], off offset:-3072 nt
	global_load_dwordx4 v[28:31], v[86:87], off offset:-2048 nt
	global_load_dwordx4 v[24:27], v[86:87], off offset:-1024 nt
	global_load_dwordx4 v[16:19], v[78:79], off offset:-4096 nt
	s_nop 0
	global_load_dwordx4 v[84:87], v[104:105], off offset:-3072 nt
	global_load_dwordx4 v[88:91], v[104:105], off offset:-2048 nt
	global_load_dwordx4 v[92:95], v[104:105], off offset:-1024 nt
	global_load_dwordx4 v[96:99], v[104:105], off nt
	s_add_i32 s1, s1, s8
	v_lshl_add_u64 v[78:79], v[78:79], 0, s[6:7]
	s_cmpk_gt_i32 s1, 0x1fff
	s_waitcnt vmcnt(16)
	v_mul_f32_e32 v82, v13, v13
	v_mul_f32_e32 v103, v15, v15
	s_waitcnt vmcnt(15)
	v_mul_f32_e32 v104, v9, v9
	v_mul_f32_e32 v105, v11, v11
	s_waitcnt vmcnt(14)
	v_mul_f32_e32 v106, v5, v5
	v_mul_f32_e32 v107, v7, v7
	s_waitcnt vmcnt(13)
	v_mul_f32_e32 v108, v1, v1
	v_mul_f32_e32 v109, v3, v3
	v_fmac_f32_e32 v82, v12, v12
	v_fmac_f32_e32 v103, v14, v14
	v_fmac_f32_e32 v104, v8, v8
	v_fmac_f32_e32 v105, v10, v10
	v_fmac_f32_e32 v106, v4, v4
	v_fmac_f32_e32 v107, v6, v6
	v_fmac_f32_e32 v108, v0, v0
	v_fmac_f32_e32 v109, v2, v2
	v_add_f32_e32 v82, v82, v103
	v_add_f32_e32 v103, v104, v105
	s_waitcnt vmcnt(3)
	v_mul_f32_e32 v104, v85, v85
	v_add_f32_e32 v105, v106, v107
	v_mul_f32_e32 v106, v87, v87
	v_add_f32_e32 v107, v108, v109
	s_waitcnt vmcnt(2)
	v_mul_f32_e32 v108, v89, v89
	v_mul_f32_e32 v109, v91, v91
	s_waitcnt vmcnt(1)
	v_mul_f32_e32 v126, v93, v93
	v_mul_f32_e32 v127, v95, v95
	v_fmac_f32_e32 v104, v84, v84
	v_fmac_f32_e32 v106, v86, v86
	v_fmac_f32_e32 v108, v88, v88
	v_fmac_f32_e32 v109, v90, v90
	s_waitcnt vmcnt(0)
	v_mul_f32_e32 v128, v97, v97
	v_mul_f32_e32 v129, v99, v99
	v_fmac_f32_e32 v126, v92, v92
	v_fmac_f32_e32 v127, v94, v94
	v_add_f32_e32 v104, v104, v106
	v_add_f32_e32 v106, v108, v109
	v_mul_f32_e32 v110, v49, v49
	v_mul_f32_e32 v111, v51, v51
	v_fmac_f32_e32 v128, v96, v96
	v_fmac_f32_e32 v129, v98, v98
	v_add_f32_e32 v108, v126, v127
	v_add_f32_e32 v104, v104, v106
	v_mul_f32_e32 v112, v45, v45
	v_mul_f32_e32 v113, v47, v47
	v_fmac_f32_e32 v110, v48, v48
	v_fmac_f32_e32 v111, v50, v50
	v_add_f32_e32 v109, v128, v129
	v_add_f32_e32 v104, v104, v108
	v_mul_f32_e32 v114, v41, v41
	v_mul_f32_e32 v115, v43, v43
	v_fmac_f32_e32 v112, v44, v44
	v_fmac_f32_e32 v113, v46, v46
	v_add_f32_e32 v110, v110, v111
	v_add_f32_e32 v104, v104, v109
	v_mul_f32_e32 v116, v37, v37
	v_mul_f32_e32 v117, v39, v39
	v_fmac_f32_e32 v114, v40, v40
	v_fmac_f32_e32 v115, v42, v42
	v_add_f32_e32 v111, v112, v113
	v_add_f32_e32 v104, v104, v110
	v_mul_f32_e32 v118, v33, v33
	v_mul_f32_e32 v119, v35, v35
	v_fmac_f32_e32 v116, v36, v36
	v_fmac_f32_e32 v117, v38, v38
	v_add_f32_e32 v112, v114, v115
	v_add_f32_e32 v104, v104, v111
	v_mul_f32_e32 v120, v29, v29
	v_mul_f32_e32 v121, v31, v31
	v_fmac_f32_e32 v118, v32, v32
	v_fmac_f32_e32 v119, v34, v34
	v_add_f32_e32 v113, v116, v117
	v_add_f32_e32 v104, v104, v112
	v_mul_f32_e32 v122, v25, v25
	v_mul_f32_e32 v123, v27, v27
	v_fmac_f32_e32 v120, v28, v28
	v_fmac_f32_e32 v121, v30, v30
	v_add_f32_e32 v114, v118, v119
	v_add_f32_e32 v104, v104, v113
	v_mul_f32_e32 v124, v17, v17
	v_mul_f32_e32 v125, v19, v19
	v_fmac_f32_e32 v122, v24, v24
	v_fmac_f32_e32 v123, v26, v26
	v_add_f32_e32 v115, v120, v121
	v_add_f32_e32 v104, v104, v114
	v_fmac_f32_e32 v124, v16, v16
	v_fmac_f32_e32 v125, v18, v18
	v_add_f32_e32 v116, v122, v123
	v_add_f32_e32 v104, v104, v115
	v_add_f32_e32 v117, v124, v125
	v_add_f32_e32 v104, v104, v116
	v_add_f32_e32 v104, v104, v117
	v_add_f32_e32 v82, v104, v82
	v_add_f32_e32 v82, v82, v103
	v_add_f32_e32 v82, v82, v105
	v_add_f32_e32 v82, v82, v107
	ds_swizzle_b32 v103, v82 offset:swizzle(SWAP,1)
	s_waitcnt lgkmcnt(0)
	v_add_f32_e32 v82, v82, v103
	ds_swizzle_b32 v103, v82 offset:swizzle(SWAP,2)
	s_waitcnt lgkmcnt(0)
	v_add_f32_e32 v82, v82, v103
	ds_swizzle_b32 v103, v82 offset:swizzle(SWAP,4)
	s_waitcnt lgkmcnt(0)
	v_add_f32_e32 v82, v82, v103
	ds_swizzle_b32 v103, v82 offset:swizzle(SWAP,8)
	s_waitcnt lgkmcnt(0)
	v_add_f32_e32 v82, v82, v103
	ds_swizzle_b32 v103, v82 offset:swizzle(SWAP,16)
	s_waitcnt lgkmcnt(0)
; __device__ __forceinline__ unsigned cvt_pk_bf16(float lo, float hi) { unsigned r; asm volatile("v_cvt_pk_bf16_f32 %0, %1, %2" : "=v"(r) : "v"(lo), "v"(hi)); return r; }
; __device__ __forceinline__ float wave_sum(float v) {
;     v += __builtin_bit_cast(float, __builtin_amdgcn_ds_swizzle(__builtin_bit_cast(int, v), (1 << 10) | 0x1f));
;     v += __builtin_bit_cast(float, __builtin_amdgcn_ds_swizzle(__builtin_bit_cast(int, v), (2 << 10) | 0x1f));
;     v += __builtin_bit_cast(float, __builtin_amdgcn_ds_swizzle(__builtin_bit_cast(int, v), (4 << 10) | 0x1f));
;     v += __builtin_bit_cast(float, __builtin_amdgcn_ds_swizzle(__builtin_bit_cast(int, v), (8 << 10) | 0x1f));
;     v += __builtin_bit_cast(float, __builtin_amdgcn_ds_swizzle(__builtin_bit_cast(int, v), (16 << 10) | 0x1f));
;     { const auto rr = __builtin_amdgcn_permlane32_swap(__float_as_uint(v), __float_as_uint(v), false, false); v = __uint_as_float(rr[0]) + __uint_as_float(rr[1]); }
;     return v;
; }
; __device__ __forceinline__ void rms_row_to_bf16(const float* xrow, const float* g, bf16_t* orow, int lane, unsigned char* o8row = nullptr) {
;     ...
;     const float rstd = 1.0f / sqrtf(wave_sum(s) * (1.f / D) + EPS);
;     u32x2* o8 = (u32x2*)orow + lane;
; #pragma unroll
;     for (int j = 0; j < 16; ++j) { const f32x4 gg = gr[64 * j]; const f32x4 y = v[j] * rstd * gg;
;         if (orow) { u32x2 w; w.x = cvt_pk_bf16(y.x, y.y); w.y = cvt_pk_bf16(y.z, y.w); o8[64 * j] = w; }
;         if (o8row) ((unsigned*)o8row)[lane + 64 * j] = pk4_i8(y.x, y.y, y.z, y.w, XN_QS); }
	v_add_f32_e32 v82, v82, v103
	v_mov_b32_e32 v103, v82
	s_nop 1
	v_permlane32_swap_b32_e32 v82, v103
	v_add_f32_e32 v82, v82, v103
	v_fmamk_f32 v82, v82, 0x39800000, v100
	v_mul_f32_e32 v103, 0x4f800000, v82
	v_cmp_gt_f32_e32 vcc, s9, v82
	s_nop 1
	v_cndmask_b32_e32 v82, v82, v103, vcc
	v_sqrt_f32_e32 v103, v82
	s_nop 0
	v_add_u32_e32 v104, -1, v103
	v_add_u32_e32 v105, 1, v103
	v_fma_f32 v106, -v104, v103, v82
	v_fma_f32 v107, -v105, v103, v82
	v_cmp_ge_f32_e64 s[4:5], 0, v106
	s_nop 1
	v_cndmask_b32_e64 v103, v103, v104, s[4:5]
	v_cmp_lt_f32_e64 s[4:5], 0, v107
	s_nop 1
	v_cndmask_b32_e64 v103, v103, v105, s[4:5]
	v_mul_f32_e32 v104, 0x37800000, v103
	v_cndmask_b32_e32 v103, v103, v104, vcc
	v_cmp_class_f32_e32 vcc, v82, v101
	s_nop 1
	v_cndmask_b32_e32 v82, v103, v82, vcc
	v_div_scale_f32 v103, s[4:5], v82, v82, 1.0
	v_rcp_f32_e32 v105, v103
	v_div_scale_f32 v104, vcc, 1.0, v82, 1.0
	v_fma_f32 v106, -v103, v105, 1.0
	v_fmac_f32_e32 v105, v106, v105
	v_mul_f32_e32 v106, v104, v105
	v_fma_f32 v107, -v103, v106, v104
	v_fmac_f32_e32 v106, v107, v105
	v_fma_f32 v103, -v103, v106, v104
	v_div_fmas_f32 v103, v103, v105, v106
	v_div_fixup_f32 v82, v103, v82, 1.0
	v_pk_mul_f32 v[84:85], v[84:85], v[82:83] op_sel_hi:[1,0]
	v_pk_mul_f32 v[86:87], v[86:87], v[82:83] op_sel_hi:[1,0]
	v_pk_mul_f32 v[20:21], v[20:21], v[84:85]
	v_pk_mul_f32 v[22:23], v[22:23], v[86:87]
	v_mul_f32_e32 v21, 0x41fe0000, v21
	v_mul_f32_e32 v20, 0x41fe0000, v20
	v_mul_f32_e32 v22, 0x41fe0000, v22
	v_mul_f32_e32 v23, 0x41fe0000, v23
	v_med3_f32 v21, v21, s12, v102
	v_med3_f32 v20, v20, s12, v102
	v_med3_f32 v22, v22, s12, v102
	v_med3_f32 v23, v23, s12, v102
	v_rndne_f32_e32 v21, v21
	v_rndne_f32_e32 v20, v20
	v_rndne_f32_e32 v22, v22
	v_rndne_f32_e32 v23, v23
	v_cvt_i32_f32_e32 v21, v21
	v_cvt_i32_f32_e32 v20, v20
	v_cvt_i32_f32_sdwa v22, v22 dst_sel:WORD_1 dst_unused:UNUSED_PAD src0_sel:DWORD
	v_cvt_i32_f32_e32 v23, v23
	v_lshlrev_b32_e32 v21, 8, v21
	v_and_b32_e32 v21, 0xff00, v21
	v_and_b32_e32 v22, 0xff0000, v22
	v_perm_b32 v20, v23, v20, s13
	v_or3_b32 v20, v20, v21, v22
	global_store_dword v[80:81], v20, off offset:-2048
	global_load_dwordx4 v[20:23], v[52:53], off offset:1024
	v_pk_mul_f32 v[88:89], v[88:89], v[82:83] op_sel_hi:[1,0]
	v_pk_mul_f32 v[90:91], v[90:91], v[82:83] op_sel_hi:[1,0]
	v_pk_mul_f32 v[92:93], v[92:93], v[82:83] op_sel_hi:[1,0]
	v_pk_mul_f32 v[94:95], v[94:95], v[82:83] op_sel_hi:[1,0]
	v_pk_mul_f32 v[96:97], v[96:97], v[82:83] op_sel_hi:[1,0]
	v_pk_mul_f32 v[98:99], v[98:99], v[82:83] op_sel_hi:[1,0]
	v_pk_mul_f32 v[48:49], v[48:49], v[82:83] op_sel_hi:[1,0]
	v_pk_mul_f32 v[50:51], v[50:51], v[82:83] op_sel_hi:[1,0]
	v_pk_mul_f32 v[44:45], v[44:45], v[82:83] op_sel_hi:[1,0]
	v_pk_mul_f32 v[46:47], v[46:47], v[82:83] op_sel_hi:[1,0]
	v_pk_mul_f32 v[40:41], v[40:41], v[82:83] op_sel_hi:[1,0]
	v_pk_mul_f32 v[42:43], v[42:43], v[82:83] op_sel_hi:[1,0]
	v_pk_mul_f32 v[36:37], v[36:37], v[82:83] op_sel_hi:[1,0]
	v_pk_mul_f32 v[38:39], v[38:39], v[82:83] op_sel_hi:[1,0]
	v_pk_mul_f32 v[32:33], v[32:33], v[82:83] op_sel_hi:[1,0]
	v_pk_mul_f32 v[34:35], v[34:35], v[82:83] op_sel_hi:[1,0]
	v_pk_mul_f32 v[28:29], v[28:29], v[82:83] op_sel_hi:[1,0]
	v_pk_mul_f32 v[30:31], v[30:31], v[82:83] op_sel_hi:[1,0]
	v_pk_mul_f32 v[24:25], v[24:25], v[82:83] op_sel_hi:[1,0]
	v_pk_mul_f32 v[26:27], v[26:27], v[82:83] op_sel_hi:[1,0]
	v_pk_mul_f32 v[16:17], v[16:17], v[82:83] op_sel_hi:[1,0]
	v_pk_mul_f32 v[18:19], v[18:19], v[82:83] op_sel_hi:[1,0]
	v_pk_mul_f32 v[12:13], v[12:13], v[82:83] op_sel_hi:[1,0]
	v_pk_mul_f32 v[14:15], v[14:15], v[82:83] op_sel_hi:[1,0]
	v_pk_mul_f32 v[8:9], v[8:9], v[82:83] op_sel_hi:[1,0]
	v_pk_mul_f32 v[10:11], v[10:11], v[82:83] op_sel_hi:[1,0]
	v_pk_mul_f32 v[4:5], v[4:5], v[82:83] op_sel_hi:[1,0]
	v_pk_mul_f32 v[6:7], v[6:7], v[82:83] op_sel_hi:[1,0]
	v_pk_mul_f32 v[0:1], v[0:1], v[82:83] op_sel_hi:[1,0]
	v_pk_mul_f32 v[2:3], v[2:3], v[82:83] op_sel_hi:[1,0]
	s_waitcnt vmcnt(0)
	v_pk_mul_f32 v[20:21], v[20:21], v[88:89]
	v_pk_mul_f32 v[22:23], v[22:23], v[90:91]
	v_mul_f32_e32 v21, 0x41fe0000, v21
	v_mul_f32_e32 v20, 0x41fe0000, v20
	v_mul_f32_e32 v22, 0x41fe0000, v22
	v_mul_f32_e32 v23, 0x41fe0000, v23
	v_med3_f32 v21, v21, s12, v102
	v_med3_f32 v20, v20, s12, v102
	v_med3_f32 v22, v22, s12, v102
	v_med3_f32 v23, v23, s12, v102
	v_rndne_f32_e32 v21, v21
	v_rndne_f32_e32 v20, v20
	v_rndne_f32_e32 v22, v22
	v_rndne_f32_e32 v23, v23
	v_cvt_i32_f32_e32 v21, v21
	v_cvt_i32_f32_e32 v20, v20
	v_cvt_i32_f32_sdwa v22, v22 dst_sel:WORD_1 dst_unused:UNUSED_PAD src0_sel:DWORD
	v_cvt_i32_f32_e32 v23, v23
	v_lshlrev_b32_e32 v21, 8, v21
	v_and_b32_e32 v21, 0xff00, v21
	v_and_b32_e32 v22, 0xff0000, v22
	v_perm_b32 v20, v23, v20, s13
	v_or3_b32 v20, v20, v21, v22
	global_store_dword v[80:81], v20, off offset:-1792
	global_load_dwordx4 v[20:23], v[52:53], off offset:2048
	s_waitcnt vmcnt(0)
	v_pk_mul_f32 v[20:21], v[20:21], v[92:93]
	v_pk_mul_f32 v[22:23], v[22:23], v[94:95]
	v_mul_f32_e32 v21, 0x41fe0000, v21
	v_mul_f32_e32 v20, 0x41fe0000, v20
	v_mul_f32_e32 v22, 0x41fe0000, v22
	v_mul_f32_e32 v23, 0x41fe0000, v23
	v_med3_f32 v21, v21, s12, v102
	v_med3_f32 v20, v20, s12, v102
	v_med3_f32 v22, v22, s12, v102
	v_med3_f32 v23, v23, s12, v102
	v_rndne_f32_e32 v21, v21
	v_rndne_f32_e32 v20, v20
	v_rndne_f32_e32 v22, v22
	v_rndne_f32_e32 v23, v23
	v_cvt_i32_f32_e32 v21, v21
	v_cvt_i32_f32_e32 v20, v20
	v_cvt_i32_f32_sdwa v22, v22 dst_sel:WORD_1 dst_unused:UNUSED_PAD src0_sel:DWORD
	v_cvt_i32_f32_e32 v23, v23
	v_lshlrev_b32_e32 v21, 8, v21
	v_and_b32_e32 v21, 0xff00, v21
	v_and_b32_e32 v22, 0xff0000, v22
	v_perm_b32 v20, v23, v20, s13
	v_or3_b32 v20, v20, v21, v22
	global_store_dword v[80:81], v20, off offset:-1536
	global_load_dwordx4 v[20:23], v[52:53], off offset:3072
	s_waitcnt vmcnt(0)
; __device__ __forceinline__ unsigned cvt_pk_bf16(float lo, float hi) { unsigned r; asm volatile("v_cvt_pk_bf16_f32 %0, %1, %2" : "=v"(r) : "v"(lo), "v"(hi)); return r; }
; __device__ __forceinline__ unsigned pk4_i8(float a, float b, float c, float d, float qs) {
;     const int q0 = (int)__builtin_rintf(fminf(fmaxf(a * qs, -127.f), 127.f)), q1 = (int)__builtin_rintf(fminf(fmaxf(b * qs, -127.f), 127.f));
;     const int q2 = (int)__builtin_rintf(fminf(fmaxf(c * qs, -127.f), 127.f)), q3 = (int)__builtin_rintf(fminf(fmaxf(d * qs, -127.f), 127.f));
;     return ((unsigned)q0 & 0xffu) | (((unsigned)q1 & 0xffu) << 8) | (((unsigned)q2 & 0xffu) << 16) | ((unsigned)q3 << 24);
; }
; __device__ __forceinline__ void rms_row_to_bf16(const float* xrow, const float* g, bf16_t* orow, int lane, unsigned char* o8row = nullptr) {
;     ...
;     for (int j = 0; j < 16; ++j) { const f32x4 gg = gr[64 * j]; const f32x4 y = v[j] * rstd * gg;
;         if (orow) { u32x2 w; w.x = cvt_pk_bf16(y.x, y.y); w.y = cvt_pk_bf16(y.z, y.w); o8[64 * j] = w; }
;         if (o8row) ((unsigned*)o8row)[lane + 64 * j] = pk4_i8(y.x, y.y, y.z, y.w, XN_QS); }
	v_pk_mul_f32 v[20:21], v[20:21], v[96:97]
	v_pk_mul_f32 v[22:23], v[22:23], v[98:99]
	v_mul_f32_e32 v21, 0x41fe0000, v21
	v_mul_f32_e32 v20, 0x41fe0000, v20
	v_mul_f32_e32 v22, 0x41fe0000, v22
	v_mul_f32_e32 v23, 0x41fe0000, v23
	v_med3_f32 v21, v21, s12, v102
	v_med3_f32 v20, v20, s12, v102
	v_med3_f32 v22, v22, s12, v102
	v_med3_f32 v23, v23, s12, v102
	v_rndne_f32_e32 v21, v21
	v_rndne_f32_e32 v20, v20
	v_rndne_f32_e32 v22, v22
	v_rndne_f32_e32 v23, v23
	v_cvt_i32_f32_e32 v21, v21
	v_cvt_i32_f32_e32 v20, v20
	v_cvt_i32_f32_sdwa v22, v22 dst_sel:WORD_1 dst_unused:UNUSED_PAD src0_sel:DWORD
	v_cvt_i32_f32_e32 v23, v23
	v_lshlrev_b32_e32 v21, 8, v21
	v_and_b32_e32 v21, 0xff00, v21
	v_and_b32_e32 v22, 0xff0000, v22
	v_perm_b32 v20, v23, v20, s13
	v_or3_b32 v20, v20, v21, v22
	global_store_dword v[80:81], v20, off offset:-1280
	global_load_dwordx4 v[20:23], v[54:55], off
	s_waitcnt vmcnt(0)
	v_pk_mul_f32 v[20:21], v[20:21], v[48:49]
	v_pk_mul_f32 v[22:23], v[22:23], v[50:51]
	v_mul_f32_e32 v21, 0x41fe0000, v21
	v_mul_f32_e32 v20, 0x41fe0000, v20
	v_mul_f32_e32 v22, 0x41fe0000, v22
	v_mul_f32_e32 v23, 0x41fe0000, v23
	v_med3_f32 v21, v21, s12, v102
	v_med3_f32 v20, v20, s12, v102
	v_med3_f32 v22, v22, s12, v102
	v_med3_f32 v23, v23, s12, v102
	v_rndne_f32_e32 v21, v21
	v_rndne_f32_e32 v20, v20
	v_rndne_f32_e32 v22, v22
	v_rndne_f32_e32 v23, v23
	v_cvt_i32_f32_e32 v21, v21
	v_cvt_i32_f32_e32 v20, v20
	v_cvt_i32_f32_sdwa v22, v22 dst_sel:WORD_1 dst_unused:UNUSED_PAD src0_sel:DWORD
	v_cvt_i32_f32_e32 v23, v23
	v_lshlrev_b32_e32 v21, 8, v21
	v_and_b32_e32 v21, 0xff00, v21
	v_and_b32_e32 v22, 0xff0000, v22
	v_perm_b32 v20, v23, v20, s13
	v_or3_b32 v20, v20, v21, v22
	global_store_dword v[80:81], v20, off offset:-1024
	global_load_dwordx4 v[20:23], v[56:57], off
	s_waitcnt vmcnt(0)
	v_pk_mul_f32 v[20:21], v[44:45], v[20:21]
	v_pk_mul_f32 v[22:23], v[46:47], v[22:23]
	v_mul_f32_e32 v21, 0x41fe0000, v21
	v_mul_f32_e32 v20, 0x41fe0000, v20
	v_mul_f32_e32 v22, 0x41fe0000, v22
	v_mul_f32_e32 v23, 0x41fe0000, v23
	v_med3_f32 v21, v21, s12, v102
	v_med3_f32 v20, v20, s12, v102
	v_med3_f32 v22, v22, s12, v102
	v_med3_f32 v23, v23, s12, v102
	v_rndne_f32_e32 v21, v21
	v_rndne_f32_e32 v20, v20
	v_rndne_f32_e32 v22, v22
	v_rndne_f32_e32 v23, v23
	v_cvt_i32_f32_e32 v21, v21
	v_cvt_i32_f32_e32 v20, v20
	v_cvt_i32_f32_sdwa v22, v22 dst_sel:WORD_1 dst_unused:UNUSED_PAD src0_sel:DWORD
	v_cvt_i32_f32_e32 v23, v23
	v_lshlrev_b32_e32 v21, 8, v21
	v_and_b32_e32 v21, 0xff00, v21
	v_and_b32_e32 v22, 0xff0000, v22
	v_perm_b32 v20, v23, v20, s13
	v_or3_b32 v20, v20, v21, v22
	global_store_dword v[80:81], v20, off offset:-768
	global_load_dwordx4 v[20:23], v[58:59], off
	s_waitcnt vmcnt(0)
	v_pk_mul_f32 v[20:21], v[40:41], v[20:21]
	v_pk_mul_f32 v[22:23], v[42:43], v[22:23]
	v_mul_f32_e32 v21, 0x41fe0000, v21
	v_mul_f32_e32 v20, 0x41fe0000, v20
	v_mul_f32_e32 v22, 0x41fe0000, v22
	v_mul_f32_e32 v23, 0x41fe0000, v23
	v_med3_f32 v21, v21, s12, v102
	v_med3_f32 v20, v20, s12, v102
	v_med3_f32 v22, v22, s12, v102
	v_med3_f32 v23, v23, s12, v102
	v_rndne_f32_e32 v21, v21
	v_rndne_f32_e32 v20, v20
	v_rndne_f32_e32 v22, v22
	v_rndne_f32_e32 v23, v23
	v_cvt_i32_f32_e32 v21, v21
	v_cvt_i32_f32_e32 v20, v20
	v_cvt_i32_f32_sdwa v22, v22 dst_sel:WORD_1 dst_unused:UNUSED_PAD src0_sel:DWORD
	v_cvt_i32_f32_e32 v23, v23
	v_lshlrev_b32_e32 v21, 8, v21
	v_and_b32_e32 v21, 0xff00, v21
	v_and_b32_e32 v22, 0xff0000, v22
	v_perm_b32 v20, v23, v20, s13
	v_or3_b32 v20, v20, v21, v22
	global_store_dword v[80:81], v20, off offset:-512
	global_load_dwordx4 v[20:23], v[60:61], off
	s_waitcnt vmcnt(0)
	v_pk_mul_f32 v[20:21], v[36:37], v[20:21]
	v_pk_mul_f32 v[22:23], v[38:39], v[22:23]
	v_mul_f32_e32 v21, 0x41fe0000, v21
	v_mul_f32_e32 v20, 0x41fe0000, v20
	v_mul_f32_e32 v22, 0x41fe0000, v22
	v_mul_f32_e32 v23, 0x41fe0000, v23
	v_med3_f32 v21, v21, s12, v102
	v_med3_f32 v20, v20, s12, v102
	v_med3_f32 v22, v22, s12, v102
	v_med3_f32 v23, v23, s12, v102
	v_rndne_f32_e32 v21, v21
	v_rndne_f32_e32 v20, v20
	v_rndne_f32_e32 v22, v22
	v_rndne_f32_e32 v23, v23
	v_cvt_i32_f32_e32 v21, v21
	v_cvt_i32_f32_e32 v20, v20
	v_cvt_i32_f32_sdwa v22, v22 dst_sel:WORD_1 dst_unused:UNUSED_PAD src0_sel:DWORD
	v_cvt_i32_f32_e32 v23, v23
	v_lshlrev_b32_e32 v21, 8, v21
	v_and_b32_e32 v21, 0xff00, v21
	v_and_b32_e32 v22, 0xff0000, v22
	v_perm_b32 v20, v23, v20, s13
	v_or3_b32 v20, v20, v21, v22
	global_store_dword v[80:81], v20, off offset:-256
	global_load_dwordx4 v[20:23], v[62:63], off
	s_waitcnt vmcnt(0)
	v_pk_mul_f32 v[20:21], v[32:33], v[20:21]
	v_pk_mul_f32 v[22:23], v[34:35], v[22:23]
	v_mul_f32_e32 v21, 0x41fe0000, v21
	v_mul_f32_e32 v20, 0x41fe0000, v20
	v_mul_f32_e32 v22, 0x41fe0000, v22
	v_mul_f32_e32 v23, 0x41fe0000, v23
	v_med3_f32 v21, v21, s12, v102
	v_med3_f32 v20, v20, s12, v102
	v_med3_f32 v22, v22, s12, v102
	v_med3_f32 v23, v23, s12, v102
	v_rndne_f32_e32 v21, v21
	v_rndne_f32_e32 v20, v20
	v_rndne_f32_e32 v22, v22
	v_rndne_f32_e32 v23, v23
	v_cvt_i32_f32_e32 v21, v21
	v_cvt_i32_f32_e32 v20, v20
	v_cvt_i32_f32_sdwa v22, v22 dst_sel:WORD_1 dst_unused:UNUSED_PAD src0_sel:DWORD
	v_cvt_i32_f32_e32 v23, v23
	v_lshlrev_b32_e32 v21, 8, v21
	v_and_b32_e32 v21, 0xff00, v21
	v_and_b32_e32 v22, 0xff0000, v22
	v_perm_b32 v20, v23, v20, s13
	v_or3_b32 v20, v20, v21, v22
	global_store_dword v[80:81], v20, off
	global_load_dwordx4 v[20:23], v[64:65], off
	s_waitcnt vmcnt(0)
; __device__ __forceinline__ unsigned cvt_pk_bf16(float lo, float hi) { unsigned r; asm volatile("v_cvt_pk_bf16_f32 %0, %1, %2" : "=v"(r) : "v"(lo), "v"(hi)); return r; }
; __device__ __forceinline__ unsigned pk4_i8(float a, float b, float c, float d, float qs) {
;     const int q0 = (int)__builtin_rintf(fminf(fmaxf(a * qs, -127.f), 127.f)), q1 = (int)__builtin_rintf(fminf(fmaxf(b * qs, -127.f), 127.f));
;     const int q2 = (int)__builtin_rintf(fminf(fmaxf(c * qs, -127.f), 127.f)), q3 = (int)__builtin_rintf(fminf(fmaxf(d * qs, -127.f), 127.f));
;     return ((unsigned)q0 & 0xffu) | (((unsigned)q1 & 0xffu) << 8) | (((unsigned)q2 & 0xffu) << 16) | ((unsigned)q3 << 24);
; }
; __device__ __forceinline__ void rms_row_to_bf16(const float* xrow, const float* g, bf16_t* orow, int lane, unsigned char* o8row = nullptr) {
;     ...
;     for (int j = 0; j < 16; ++j) { const f32x4 gg = gr[64 * j]; const f32x4 y = v[j] * rstd * gg;
;         if (orow) { u32x2 w; w.x = cvt_pk_bf16(y.x, y.y); w.y = cvt_pk_bf16(y.z, y.w); o8[64 * j] = w; }
;         if (o8row) ((unsigned*)o8row)[lane + 64 * j] = pk4_i8(y.x, y.y, y.z, y.w, XN_QS); }
	v_pk_mul_f32 v[20:21], v[28:29], v[20:21]
	v_pk_mul_f32 v[22:23], v[30:31], v[22:23]
	v_mul_f32_e32 v21, 0x41fe0000, v21
	v_mul_f32_e32 v20, 0x41fe0000, v20
	v_mul_f32_e32 v22, 0x41fe0000, v22
	v_mul_f32_e32 v23, 0x41fe0000, v23
	v_med3_f32 v21, v21, s12, v102
	v_med3_f32 v20, v20, s12, v102
	v_med3_f32 v22, v22, s12, v102
	v_med3_f32 v23, v23, s12, v102
	v_rndne_f32_e32 v21, v21
	v_rndne_f32_e32 v20, v20
	v_rndne_f32_e32 v22, v22
	v_rndne_f32_e32 v23, v23
	v_cvt_i32_f32_e32 v21, v21
	v_cvt_i32_f32_e32 v20, v20
	v_cvt_i32_f32_sdwa v22, v22 dst_sel:WORD_1 dst_unused:UNUSED_PAD src0_sel:DWORD
	v_cvt_i32_f32_e32 v23, v23
	v_lshlrev_b32_e32 v21, 8, v21
	v_and_b32_e32 v21, 0xff00, v21
	v_and_b32_e32 v22, 0xff0000, v22
	v_perm_b32 v20, v23, v20, s13
	v_or3_b32 v20, v20, v21, v22
	global_store_dword v[80:81], v20, off offset:256
	global_load_dwordx4 v[20:23], v[66:67], off
	s_waitcnt vmcnt(0)
	v_pk_mul_f32 v[20:21], v[24:25], v[20:21]
	v_pk_mul_f32 v[22:23], v[26:27], v[22:23]
	v_mul_f32_e32 v21, 0x41fe0000, v21
	v_mul_f32_e32 v20, 0x41fe0000, v20
	v_mul_f32_e32 v22, 0x41fe0000, v22
	v_mul_f32_e32 v23, 0x41fe0000, v23
	v_med3_f32 v21, v21, s12, v102
	v_med3_f32 v20, v20, s12, v102
	v_med3_f32 v22, v22, s12, v102
	v_med3_f32 v23, v23, s12, v102
	v_rndne_f32_e32 v21, v21
	v_rndne_f32_e32 v20, v20
	v_rndne_f32_e32 v22, v22
	v_rndne_f32_e32 v23, v23
	v_cvt_i32_f32_e32 v21, v21
	v_cvt_i32_f32_e32 v20, v20
	v_cvt_i32_f32_sdwa v22, v22 dst_sel:WORD_1 dst_unused:UNUSED_PAD src0_sel:DWORD
	v_cvt_i32_f32_e32 v23, v23
	v_lshlrev_b32_e32 v21, 8, v21
	v_and_b32_e32 v21, 0xff00, v21
	v_and_b32_e32 v22, 0xff0000, v22
	v_perm_b32 v20, v23, v20, s13
	v_or3_b32 v20, v20, v21, v22
	global_store_dword v[80:81], v20, off offset:512
	global_load_dwordx4 v[20:23], v[68:69], off
	s_waitcnt vmcnt(0)
	v_pk_mul_f32 v[16:17], v[16:17], v[20:21]
	v_pk_mul_f32 v[18:19], v[18:19], v[22:23]
	v_mul_f32_e32 v17, 0x41fe0000, v17
	v_mul_f32_e32 v16, 0x41fe0000, v16
	v_mul_f32_e32 v18, 0x41fe0000, v18
	v_mul_f32_e32 v19, 0x41fe0000, v19
	v_med3_f32 v17, v17, s12, v102
	v_med3_f32 v16, v16, s12, v102
	v_med3_f32 v18, v18, s12, v102
	v_med3_f32 v19, v19, s12, v102
	v_rndne_f32_e32 v17, v17
	v_rndne_f32_e32 v16, v16
	v_rndne_f32_e32 v18, v18
	v_rndne_f32_e32 v19, v19
	v_cvt_i32_f32_e32 v17, v17
	v_cvt_i32_f32_e32 v16, v16
	v_cvt_i32_f32_sdwa v18, v18 dst_sel:WORD_1 dst_unused:UNUSED_PAD src0_sel:DWORD
	v_cvt_i32_f32_e32 v19, v19
	v_lshlrev_b32_e32 v17, 8, v17
	v_and_b32_e32 v17, 0xff00, v17
	v_and_b32_e32 v18, 0xff0000, v18
	v_perm_b32 v16, v19, v16, s13
	v_or3_b32 v16, v16, v17, v18
	global_store_dword v[80:81], v16, off offset:768
	global_load_dwordx4 v[16:19], v[70:71], off
	s_waitcnt vmcnt(0)
	v_pk_mul_f32 v[12:13], v[12:13], v[16:17]
	v_pk_mul_f32 v[14:15], v[14:15], v[18:19]
	v_mul_f32_e32 v13, 0x41fe0000, v13
	v_mul_f32_e32 v12, 0x41fe0000, v12
	v_mul_f32_e32 v14, 0x41fe0000, v14
	v_mul_f32_e32 v15, 0x41fe0000, v15
	v_med3_f32 v13, v13, s12, v102
	v_med3_f32 v12, v12, s12, v102
	v_med3_f32 v14, v14, s12, v102
	v_med3_f32 v15, v15, s12, v102
	v_rndne_f32_e32 v13, v13
	v_rndne_f32_e32 v12, v12
	v_rndne_f32_e32 v14, v14
	v_rndne_f32_e32 v15, v15
	v_cvt_i32_f32_e32 v13, v13
	v_cvt_i32_f32_e32 v12, v12
	v_cvt_i32_f32_sdwa v14, v14 dst_sel:WORD_1 dst_unused:UNUSED_PAD src0_sel:DWORD
	v_cvt_i32_f32_e32 v15, v15
	v_lshlrev_b32_e32 v13, 8, v13
	v_and_b32_e32 v13, 0xff00, v13
	v_and_b32_e32 v14, 0xff0000, v14
	v_perm_b32 v12, v15, v12, s13
	v_or3_b32 v12, v12, v13, v14
	global_store_dword v[80:81], v12, off offset:1024
	global_load_dwordx4 v[12:15], v[72:73], off
	s_waitcnt vmcnt(0)
	v_pk_mul_f32 v[8:9], v[8:9], v[12:13]
	v_pk_mul_f32 v[10:11], v[10:11], v[14:15]
	v_mul_f32_e32 v9, 0x41fe0000, v9
	v_mul_f32_e32 v8, 0x41fe0000, v8
	v_mul_f32_e32 v10, 0x41fe0000, v10
	v_mul_f32_e32 v11, 0x41fe0000, v11
	v_med3_f32 v9, v9, s12, v102
	v_med3_f32 v8, v8, s12, v102
	v_med3_f32 v10, v10, s12, v102
	v_med3_f32 v11, v11, s12, v102
	v_rndne_f32_e32 v9, v9
	v_rndne_f32_e32 v8, v8
	v_rndne_f32_e32 v10, v10
	v_rndne_f32_e32 v11, v11
	v_cvt_i32_f32_e32 v9, v9
	v_cvt_i32_f32_e32 v8, v8
	v_cvt_i32_f32_sdwa v10, v10 dst_sel:WORD_1 dst_unused:UNUSED_PAD src0_sel:DWORD
	v_cvt_i32_f32_e32 v11, v11
	v_lshlrev_b32_e32 v9, 8, v9
	v_and_b32_e32 v9, 0xff00, v9
	v_and_b32_e32 v10, 0xff0000, v10
	v_perm_b32 v8, v11, v8, s13
	v_or3_b32 v8, v8, v9, v10
	global_store_dword v[80:81], v8, off offset:1280
	global_load_dwordx4 v[8:11], v[74:75], off
	s_waitcnt vmcnt(0)
	v_pk_mul_f32 v[4:5], v[4:5], v[8:9]
	v_pk_mul_f32 v[6:7], v[6:7], v[10:11]
	v_mul_f32_e32 v5, 0x41fe0000, v5
	v_mul_f32_e32 v4, 0x41fe0000, v4
	v_mul_f32_e32 v6, 0x41fe0000, v6
	v_mul_f32_e32 v7, 0x41fe0000, v7
	v_med3_f32 v5, v5, s12, v102
	v_med3_f32 v4, v4, s12, v102
	v_med3_f32 v6, v6, s12, v102
	v_med3_f32 v7, v7, s12, v102
	v_rndne_f32_e32 v5, v5
	v_rndne_f32_e32 v4, v4
	v_rndne_f32_e32 v6, v6
	v_rndne_f32_e32 v7, v7
	v_cvt_i32_f32_e32 v5, v5
	v_cvt_i32_f32_e32 v4, v4
	v_cvt_i32_f32_sdwa v6, v6 dst_sel:WORD_1 dst_unused:UNUSED_PAD src0_sel:DWORD
	v_cvt_i32_f32_e32 v7, v7
	v_lshlrev_b32_e32 v5, 8, v5
	v_and_b32_e32 v5, 0xff00, v5
	v_and_b32_e32 v6, 0xff0000, v6
	v_perm_b32 v4, v7, v4, s13
	v_or3_b32 v4, v4, v5, v6
	global_store_dword v[80:81], v4, off offset:1536
	global_load_dwordx4 v[4:7], v[76:77], off
	s_waitcnt vmcnt(0)
	v_pk_mul_f32 v[0:1], v[0:1], v[4:5]
	v_pk_mul_f32 v[2:3], v[2:3], v[6:7]
	v_mul_f32_e32 v1, 0x41fe0000, v1
	v_mul_f32_e32 v0, 0x41fe0000, v0
	v_mul_f32_e32 v2, 0x41fe0000, v2
	v_mul_f32_e32 v3, 0x41fe0000, v3
	v_med3_f32 v1, v1, s12, v102
	v_med3_f32 v0, v0, s12, v102
	v_med3_f32 v2, v2, s12, v102
	v_med3_f32 v3, v3, s12, v102
	v_rndne_f32_e32 v1, v1
	v_rndne_f32_e32 v0, v0
	v_rndne_f32_e32 v2, v2
	v_rndne_f32_e32 v3, v3
	v_cvt_i32_f32_e32 v1, v1
	v_cvt_i32_f32_e32 v0, v0
	v_cvt_i32_f32_sdwa v2, v2 dst_sel:WORD_1 dst_unused:UNUSED_PAD src0_sel:DWORD
	v_cvt_i32_f32_e32 v3, v3
	v_lshlrev_b32_e32 v1, 8, v1
	v_and_b32_e32 v1, 0xff00, v1
	v_and_b32_e32 v2, 0xff0000, v2
	v_perm_b32 v0, v3, v0, s13
	v_or3_b32 v0, v0, v1, v2
	global_store_dword v[80:81], v0, off offset:1792
	v_lshl_add_u64 v[80:81], v[80:81], 0, s[10:11]
	s_cbranch_scc0 .LBB0_89

; __global__ void __launch_bounds__(NWAVES * 64, 2) fwd(Args args) {
;     ...
;                 for (int idx = vcu * (NWAVES * 64) + tid; idx < (MG / 64) * 2048; idx += G * NWAVES * 64) {
;                     const int T = idx >> 11, hi_ = (idx >> 10) & 1, cg = idx & 1023, h = cg >> 5, cl = (cg & 31) * 4;
;                     const unsigned char* src = V8 + (size_t)(T * 64 + 4 * hi_) * 4096 + 4 * cg;
;                     int wa[16], wb[16];
; #pragma unroll
;                     for (int r = 0; r < 16; ++r) { const int k_ = (r & 3) + 8 * (r >> 2); wa[r] = *(const int*)(src + (size_t)k_ * 4096); wb[r] = *(const int*)(src + (size_t)(32 + k_) * 4096); }
;                     unsigned char* dst = VP + ((size_t)h * (MG / 64) + T) * 8192;
.LBB0_566:
	v_ashrrev_i32_e32 v0, 11, v43
	v_bfe_u32 v40, v43, 10, 1
	v_lshlrev_b32_e32 v1, 6, v0
	v_lshl_or_b32 v4, v40, 2, v1
	v_ashrrev_i32_e32 v5, 31, v4
	v_lshlrev_b64 v[4:5], 12, v[4:5]
	v_lshl_add_u64 v[4:5], v[36:37], 0, v[4:5]
	v_and_b32_e32 v2, 0xffc, v48
	v_lshl_add_u64 v[4:5], v[4:5], 0, v[2:3]
	s_mov_b32 s1, 0x21000
	v_add_co_u32_e32 v6, vcc, s1, v4
	s_mov_b32 s1, 0x23000
	s_nop 0
	v_addc_co_u32_e32 v7, vcc, 0, v5, vcc
	v_add_co_u32_e32 v8, vcc, s21, v4
	global_load_dword v50, v[4:5], off nt
	global_load_dword v51, v[6:7], off offset:-4096 nt
	v_addc_co_u32_e32 v9, vcc, 0, v5, vcc
	global_load_dword v52, v[8:9], off offset:-4096 nt
	global_load_dword v53, v[6:7], off nt
	global_load_dword v54, v[8:9], off nt
	v_add_co_u32_e32 v6, vcc, s1, v4
	s_mov_b32 s1, 0x29000
	s_nop 0
	v_addc_co_u32_e32 v7, vcc, 0, v5, vcc
	v_add_co_u32_e32 v8, vcc, s74, v4
	global_load_dword v55, v[6:7], off offset:-4096 nt
	s_nop 0
	v_addc_co_u32_e32 v9, vcc, 0, v5, vcc
	global_load_dword v56, v[8:9], off nt
	global_load_dword v57, v[6:7], off nt
	v_add_co_u32_e32 v6, vcc, s3, v4
	v_and_b32_e32 v2, 0xf80, v48
	s_nop 0
	v_addc_co_u32_e32 v7, vcc, 0, v5, vcc
	v_add_co_u32_e32 v8, vcc, s1, v4
	global_load_dword v58, v[6:7], off offset:-4096 nt
	s_nop 0
	v_addc_co_u32_e32 v9, vcc, 0, v5, vcc
	global_load_dword v59, v[8:9], off offset:-4096 nt
	global_load_dword v60, v[6:7], off nt
	global_load_dword v61, v[8:9], off nt
	v_add_co_u32_e32 v6, vcc, s86, v4
	s_mov_b32 s1, 0x2b000
	s_nop 0
	v_addc_co_u32_e32 v7, vcc, 0, v5, vcc
	v_add_co_u32_e32 v8, vcc, s1, v4
	global_load_dword v62, v[6:7], off offset:-4096 nt
	s_nop 0
	v_addc_co_u32_e32 v9, vcc, 0, v5, vcc
	global_load_dword v63, v[8:9], off offset:-4096 nt
	global_load_dword v64, v[6:7], off nt
	global_load_dword v65, v[8:9], off nt
	v_add_co_u32_e32 v6, vcc, s87, v4
	s_mov_b32 s1, 0x31000
	s_nop 0
	v_addc_co_u32_e32 v7, vcc, 0, v5, vcc
	v_add_co_u32_e32 v8, vcc, s1, v4
	global_load_dword v66, v[6:7], off offset:-4096 nt
	s_nop 0
	v_addc_co_u32_e32 v9, vcc, 0, v5, vcc
	global_load_dword v67, v[8:9], off offset:-4096 nt
	global_load_dword v68, v[6:7], off nt
	global_load_dword v69, v[8:9], off nt
	v_add_co_u32_e32 v6, vcc, s88, v4
	s_mov_b32 s1, 0x33000
	s_nop 0
	v_addc_co_u32_e32 v7, vcc, 0, v5, vcc
	v_add_co_u32_e32 v8, vcc, s1, v4
	global_load_dword v70, v[6:7], off offset:-4096 nt
	s_nop 0
	v_addc_co_u32_e32 v9, vcc, 0, v5, vcc
	global_load_dword v71, v[8:9], off offset:-4096 nt
	global_load_dword v72, v[6:7], off nt
	global_load_dword v73, v[8:9], off nt
	v_add_co_u32_e32 v6, vcc, s89, v4
	s_mov_b32 s1, 0x39000
	s_nop 0
	v_addc_co_u32_e32 v7, vcc, 0, v5, vcc
	v_add_co_u32_e32 v8, vcc, s1, v4
	global_load_dword v74, v[6:7], off offset:-4096 nt
	s_nop 0
	v_addc_co_u32_e32 v9, vcc, 0, v5, vcc
	global_load_dword v75, v[8:9], off offset:-4096 nt
	global_load_dword v76, v[6:7], off nt
	global_load_dword v77, v[8:9], off nt
	v_add_co_u32_e32 v6, vcc, s90, v4
	s_mov_b32 s1, 0x3b000
	s_nop 0
	v_addc_co_u32_e32 v7, vcc, 0, v5, vcc
	v_add_co_u32_e32 v4, vcc, s1, v4
	global_load_dword v78, v[6:7], off offset:-4096 nt
	s_nop 0
	v_addc_co_u32_e32 v5, vcc, 0, v5, vcc
	global_load_dword v80, v[4:5], off offset:-4096 nt
	global_load_dword v81, v[6:7], off nt
	global_load_dword v79, v[4:5], off nt
	s_waitcnt vmcnt(31)
	v_cvt_f32_fp8_e32 v4, v50
	s_waitcnt vmcnt(30)
	v_cvt_f32_fp8_e32 v20, v51
	s_waitcnt vmcnt(27)
	v_cvt_f32_fp8_e32 v6, v54
	v_cvt_f32_fp8_e32 v5, v52
	v_cvt_f32_fp8_e32 v21, v53
	v_ashrrev_i32_e32 v1, 31, v0
	v_lshl_add_u64 v[0:1], v[2:3], 0, v[0:1]
	v_lshlrev_b64 v[0:1], 13, v[0:1]
	v_pk_mul_f32 v[4:5], v[4:5], s[20:21] op_sel_hi:[1,0]
	v_pk_mul_f32 v[20:21], v[20:21], s[20:21] op_sel_hi:[1,0]
	s_waitcnt vmcnt(26)
	v_cvt_f32_fp8_e32 v22, v55
	v_and_b32_e32 v2, 0x1f00, v46
	s_waitcnt vmcnt(25)
	v_cvt_f32_fp8_e32 v7, v56
	s_waitcnt vmcnt(24)
	v_cvt_f32_fp8_e32 v23, v57
	v_lshl_add_u64 v[0:1], v[38:39], 0, v[0:1]
	v_add_u32_e32 v43, v43, v44
	v_pk_mul_f32 v[6:7], v[6:7], s[20:21] op_sel_hi:[1,0]
	v_pk_mul_f32 v[22:23], v[22:23], s[20:21] op_sel_hi:[1,0]
	s_mov_b32 s1, 0x3ffff
	v_cmp_lt_i32_e32 vcc, s1, v43
	v_add_u32_e32 v46, v46, v47
	s_waitcnt vmcnt(23)
	v_cvt_f32_fp8_e32 v8, v58
	s_waitcnt vmcnt(22)
	v_cvt_f32_fp8_e32 v24, v59
	s_waitcnt vmcnt(21)
	v_cvt_f32_fp8_e32 v9, v60
	s_waitcnt vmcnt(20)
	v_cvt_f32_fp8_e32 v25, v61
	v_add_u32_e32 v48, v48, v49
	s_or_b64 s[34:35], vcc, s[34:35]
	v_pk_mul_f32 v[8:9], v[8:9], s[20:21] op_sel_hi:[1,0]
	v_pk_mul_f32 v[24:25], v[24:25], s[20:21] op_sel_hi:[1,0]
	s_waitcnt vmcnt(19)
	v_cvt_f32_fp8_e32 v10, v62
	s_waitcnt vmcnt(18)
	v_cvt_f32_fp8_e32 v26, v63
	s_waitcnt vmcnt(17)
	v_cvt_f32_fp8_e32 v11, v64
	s_waitcnt vmcnt(16)
	v_cvt_f32_fp8_e32 v27, v65
	v_pk_mul_f32 v[10:11], v[10:11], s[20:21] op_sel_hi:[1,0]
	v_pk_mul_f32 v[26:27], v[26:27], s[20:21] op_sel_hi:[1,0]
	s_waitcnt vmcnt(15)
	v_cvt_f32_fp8_e32 v12, v66
	s_waitcnt vmcnt(14)
	v_cvt_f32_fp8_e32 v28, v67
	s_waitcnt vmcnt(13)
	v_cvt_f32_fp8_e32 v13, v68
	s_waitcnt vmcnt(12)
	v_cvt_f32_fp8_e32 v29, v69
	v_pk_mul_f32 v[12:13], v[12:13], s[20:21] op_sel_hi:[1,0]
	v_pk_mul_f32 v[28:29], v[28:29], s[20:21] op_sel_hi:[1,0]
	s_waitcnt vmcnt(11)
	v_cvt_f32_fp8_e32 v14, v70
	s_waitcnt vmcnt(10)
	v_cvt_f32_fp8_e32 v30, v71
	s_waitcnt vmcnt(9)
	v_cvt_f32_fp8_e32 v15, v72
	s_waitcnt vmcnt(8)
	v_cvt_f32_fp8_e32 v31, v73
	v_pk_mul_f32 v[14:15], v[14:15], s[20:21] op_sel_hi:[1,0]
	v_pk_mul_f32 v[30:31], v[30:31], s[20:21] op_sel_hi:[1,0]
	s_waitcnt vmcnt(7)
	v_cvt_f32_fp8_e32 v16, v74
	s_waitcnt vmcnt(6)
	v_cvt_f32_fp8_e32 v32, v75
	s_waitcnt vmcnt(5)
	v_cvt_f32_fp8_e32 v17, v76
	s_waitcnt vmcnt(4)
; __global__ void __launch_bounds__(NWAVES * 64, 2) fwd(Args args) {
;     ...
;                     V6_COL(0) V6_COL(1) V6_COL(2) V6_COL(3)
	v_cvt_f32_fp8_e32 v33, v77
	v_pk_mul_f32 v[16:17], v[16:17], s[20:21] op_sel_hi:[1,0]
	v_pk_mul_f32 v[32:33], v[32:33], s[20:21] op_sel_hi:[1,0]
	s_waitcnt vmcnt(3)
	v_cvt_f32_fp8_e32 v18, v78
	s_waitcnt vmcnt(2)
	v_cvt_f32_fp8_e32 v34, v80
	s_waitcnt vmcnt(1)
	v_cvt_f32_fp8_e32 v19, v81
	s_waitcnt vmcnt(0)
	v_cvt_f32_fp8_e32 v35, v79
	v_pk_mul_f32 v[18:19], v[18:19], s[20:21] op_sel_hi:[1,0]
	v_pk_mul_f32 v[34:35], v[34:35], s[20:21] op_sel_hi:[1,0]
	s_nop 0
	v_cvt_scalef32_2xpk16_fp6_f32 v[82:87], v[4:19], v[20:35], 1.0
	v_lshlrev_b32_e32 v6, 1, v40
	v_lshl_add_u64 v[4:5], v[0:1], 0, v[2:3]
	v_xor_b32_e32 v0, v6, v45
	v_bitop3_b32 v6, v6, v45, 1 bitop3:0x36
	v_lshlrev_b32_e32 v2, 4, v0
	v_lshlrev_b32_e32 v6, 4, v6
	v_mov_b32_e32 v7, v3
	v_lshl_add_u64 v[40:41], v[4:5], 0, v[2:3]
	v_mov_b32_e32 v0, v86
	v_mov_b32_e32 v1, v87
	v_mov_b32_e32 v2, v3
	v_lshl_add_u64 v[88:89], v[4:5], 0, v[6:7]
	global_store_dwordx4 v[88:89], v[0:3], off
	v_cvt_f32_fp8_sdwa v20, v51 src0_sel:BYTE_1
	v_cvt_f32_fp8_sdwa v21, v53 src0_sel:BYTE_1
	v_cvt_f32_fp8_sdwa v0, v50 src0_sel:BYTE_1
	v_cvt_f32_fp8_sdwa v1, v52 src0_sel:BYTE_1
	v_cvt_f32_fp8_sdwa v4, v54 src0_sel:BYTE_1
	v_cvt_f32_fp8_sdwa v22, v55 src0_sel:BYTE_1
	v_cvt_f32_fp8_sdwa v5, v56 src0_sel:BYTE_1
	v_cvt_f32_fp8_sdwa v23, v57 src0_sel:BYTE_1
	v_cvt_f32_fp8_sdwa v6, v58 src0_sel:BYTE_1
	v_cvt_f32_fp8_sdwa v24, v59 src0_sel:BYTE_1
	v_cvt_f32_fp8_sdwa v7, v60 src0_sel:BYTE_1
	v_cvt_f32_fp8_sdwa v25, v61 src0_sel:BYTE_1
	v_cvt_f32_fp8_sdwa v8, v62 src0_sel:BYTE_1
	v_cvt_f32_fp8_sdwa v26, v63 src0_sel:BYTE_1
	v_cvt_f32_fp8_sdwa v9, v64 src0_sel:BYTE_1
	v_cvt_f32_fp8_sdwa v27, v65 src0_sel:BYTE_1
	v_cvt_f32_fp8_sdwa v10, v66 src0_sel:BYTE_1
	v_cvt_f32_fp8_sdwa v28, v67 src0_sel:BYTE_1
	v_cvt_f32_fp8_sdwa v11, v68 src0_sel:BYTE_1
	v_cvt_f32_fp8_sdwa v29, v69 src0_sel:BYTE_1
	v_cvt_f32_fp8_sdwa v12, v70 src0_sel:BYTE_1
	v_cvt_f32_fp8_sdwa v30, v71 src0_sel:BYTE_1
	v_cvt_f32_fp8_sdwa v13, v72 src0_sel:BYTE_1
	v_cvt_f32_fp8_sdwa v31, v73 src0_sel:BYTE_1
	v_cvt_f32_fp8_sdwa v14, v74 src0_sel:BYTE_1
	v_cvt_f32_fp8_sdwa v32, v75 src0_sel:BYTE_1
	v_cvt_f32_fp8_sdwa v15, v76 src0_sel:BYTE_1
	v_cvt_f32_fp8_sdwa v33, v77 src0_sel:BYTE_1
	v_cvt_f32_fp8_sdwa v16, v78 src0_sel:BYTE_1
	v_cvt_f32_fp8_sdwa v34, v80 src0_sel:BYTE_1
	v_cvt_f32_fp8_sdwa v17, v81 src0_sel:BYTE_1
	v_cvt_f32_fp8_sdwa v35, v79 src0_sel:BYTE_1
	global_store_dwordx4 v[40:41], v[82:85], off
	v_pk_mul_f32 v[32:33], v[32:33], s[20:21] op_sel_hi:[1,0]
	v_pk_mul_f32 v[18:19], v[16:17], s[20:21] op_sel_hi:[1,0]
	v_pk_mul_f32 v[16:17], v[14:15], s[20:21] op_sel_hi:[1,0]
	v_pk_mul_f32 v[14:15], v[12:13], s[20:21] op_sel_hi:[1,0]
	v_pk_mul_f32 v[12:13], v[10:11], s[20:21] op_sel_hi:[1,0]
	v_pk_mul_f32 v[10:11], v[8:9], s[20:21] op_sel_hi:[1,0]
	v_pk_mul_f32 v[8:9], v[6:7], s[20:21] op_sel_hi:[1,0]
	v_pk_mul_f32 v[6:7], v[4:5], s[20:21] op_sel_hi:[1,0]
	v_pk_mul_f32 v[4:5], v[0:1], s[20:21] op_sel_hi:[1,0]
	v_pk_mul_f32 v[34:35], v[34:35], s[20:21] op_sel_hi:[1,0]
	v_pk_mul_f32 v[30:31], v[30:31], s[20:21] op_sel_hi:[1,0]
	v_pk_mul_f32 v[28:29], v[28:29], s[20:21] op_sel_hi:[1,0]
	v_pk_mul_f32 v[26:27], v[26:27], s[20:21] op_sel_hi:[1,0]
	v_pk_mul_f32 v[24:25], v[24:25], s[20:21] op_sel_hi:[1,0]
	v_pk_mul_f32 v[22:23], v[22:23], s[20:21] op_sel_hi:[1,0]
	v_pk_mul_f32 v[20:21], v[20:21], s[20:21] op_sel_hi:[1,0]
	s_nop 0
	v_cvt_scalef32_2xpk16_fp6_f32 v[82:87], v[4:19], v[20:35], 1.0
	v_cvt_f32_fp8_sdwa v20, v51 src0_sel:BYTE_2
	v_mov_b32_e32 v0, v86
	v_mov_b32_e32 v1, v87
	global_store_dwordx4 v[88:89], v[0:3], off offset:64
	v_cvt_f32_fp8_sdwa v21, v53 src0_sel:BYTE_2
	v_cvt_f32_fp8_sdwa v4, v54 src0_sel:BYTE_2
	v_cvt_f32_fp8_sdwa v0, v50 src0_sel:BYTE_2
	v_cvt_f32_fp8_sdwa v1, v52 src0_sel:BYTE_2
	v_cvt_f32_fp8_sdwa v22, v55 src0_sel:BYTE_2
	v_cvt_f32_fp8_sdwa v5, v56 src0_sel:BYTE_2
	v_cvt_f32_fp8_sdwa v23, v57 src0_sel:BYTE_2
	v_cvt_f32_fp8_sdwa v6, v58 src0_sel:BYTE_2
	v_cvt_f32_fp8_sdwa v24, v59 src0_sel:BYTE_2
	v_cvt_f32_fp8_sdwa v7, v60 src0_sel:BYTE_2
	v_cvt_f32_fp8_sdwa v25, v61 src0_sel:BYTE_2
	v_cvt_f32_fp8_sdwa v8, v62 src0_sel:BYTE_2
	v_cvt_f32_fp8_sdwa v26, v63 src0_sel:BYTE_2
	v_cvt_f32_fp8_sdwa v9, v64 src0_sel:BYTE_2
	v_cvt_f32_fp8_sdwa v27, v65 src0_sel:BYTE_2
	v_cvt_f32_fp8_sdwa v10, v66 src0_sel:BYTE_2
	v_cvt_f32_fp8_sdwa v28, v67 src0_sel:BYTE_2
	v_cvt_f32_fp8_sdwa v11, v68 src0_sel:BYTE_2
	v_cvt_f32_fp8_sdwa v29, v69 src0_sel:BYTE_2
; __global__ void __launch_bounds__(NWAVES * 64, 2) fwd(Args args) {
;     ...
;                     V6_COL(0) V6_COL(1) V6_COL(2) V6_COL(3)
	v_cvt_f32_fp8_sdwa v12, v70 src0_sel:BYTE_2
	v_cvt_f32_fp8_sdwa v30, v71 src0_sel:BYTE_2
	v_cvt_f32_fp8_sdwa v13, v72 src0_sel:BYTE_2
	v_cvt_f32_fp8_sdwa v31, v73 src0_sel:BYTE_2
	v_cvt_f32_fp8_sdwa v14, v74 src0_sel:BYTE_2
	v_cvt_f32_fp8_sdwa v32, v75 src0_sel:BYTE_2
	v_cvt_f32_fp8_sdwa v15, v76 src0_sel:BYTE_2
	v_cvt_f32_fp8_sdwa v33, v77 src0_sel:BYTE_2
	v_cvt_f32_fp8_sdwa v16, v78 src0_sel:BYTE_2
	v_cvt_f32_fp8_sdwa v34, v80 src0_sel:BYTE_2
	v_cvt_f32_fp8_sdwa v17, v81 src0_sel:BYTE_2
	v_cvt_f32_fp8_sdwa v35, v79 src0_sel:BYTE_2
	global_store_dwordx4 v[40:41], v[82:85], off offset:64
	v_pk_mul_f32 v[32:33], v[32:33], s[20:21] op_sel_hi:[1,0]
	v_pk_mul_f32 v[18:19], v[16:17], s[20:21] op_sel_hi:[1,0]
	v_pk_mul_f32 v[16:17], v[14:15], s[20:21] op_sel_hi:[1,0]
	v_pk_mul_f32 v[14:15], v[12:13], s[20:21] op_sel_hi:[1,0]
	v_pk_mul_f32 v[12:13], v[10:11], s[20:21] op_sel_hi:[1,0]
	v_pk_mul_f32 v[10:11], v[8:9], s[20:21] op_sel_hi:[1,0]
	v_pk_mul_f32 v[8:9], v[6:7], s[20:21] op_sel_hi:[1,0]
	v_pk_mul_f32 v[6:7], v[4:5], s[20:21] op_sel_hi:[1,0]
	v_pk_mul_f32 v[4:5], v[0:1], s[20:21] op_sel_hi:[1,0]
	v_pk_mul_f32 v[34:35], v[34:35], s[20:21] op_sel_hi:[1,0]
	v_pk_mul_f32 v[30:31], v[30:31], s[20:21] op_sel_hi:[1,0]
	v_pk_mul_f32 v[28:29], v[28:29], s[20:21] op_sel_hi:[1,0]
	v_pk_mul_f32 v[26:27], v[26:27], s[20:21] op_sel_hi:[1,0]
	v_pk_mul_f32 v[24:25], v[24:25], s[20:21] op_sel_hi:[1,0]
	v_pk_mul_f32 v[22:23], v[22:23], s[20:21] op_sel_hi:[1,0]
	v_pk_mul_f32 v[20:21], v[20:21], s[20:21] op_sel_hi:[1,0]
	s_nop 0
	v_cvt_scalef32_2xpk16_fp6_f32 v[82:87], v[4:19], v[20:35], 1.0
	v_cvt_f32_fp8_sdwa v20, v51 src0_sel:BYTE_3
	v_mov_b32_e32 v0, v86
	v_mov_b32_e32 v1, v87
	global_store_dwordx4 v[88:89], v[0:3], off offset:128
	v_cvt_f32_fp8_sdwa v21, v53 src0_sel:BYTE_3
	v_cvt_f32_fp8_sdwa v4, v54 src0_sel:BYTE_3
	v_cvt_f32_fp8_sdwa v0, v50 src0_sel:BYTE_3
	v_cvt_f32_fp8_sdwa v1, v52 src0_sel:BYTE_3
	v_cvt_f32_fp8_sdwa v22, v55 src0_sel:BYTE_3
	v_cvt_f32_fp8_sdwa v5, v56 src0_sel:BYTE_3
	v_cvt_f32_fp8_sdwa v23, v57 src0_sel:BYTE_3
	v_cvt_f32_fp8_sdwa v6, v58 src0_sel:BYTE_3
	v_cvt_f32_fp8_sdwa v24, v59 src0_sel:BYTE_3
	v_cvt_f32_fp8_sdwa v7, v60 src0_sel:BYTE_3
	v_cvt_f32_fp8_sdwa v25, v61 src0_sel:BYTE_3
	v_cvt_f32_fp8_sdwa v8, v62 src0_sel:BYTE_3
	v_cvt_f32_fp8_sdwa v26, v63 src0_sel:BYTE_3
	v_cvt_f32_fp8_sdwa v9, v64 src0_sel:BYTE_3
	v_cvt_f32_fp8_sdwa v27, v65 src0_sel:BYTE_3
	v_cvt_f32_fp8_sdwa v10, v66 src0_sel:BYTE_3
	v_cvt_f32_fp8_sdwa v28, v67 src0_sel:BYTE_3
	v_cvt_f32_fp8_sdwa v11, v68 src0_sel:BYTE_3
	v_cvt_f32_fp8_sdwa v29, v69 src0_sel:BYTE_3
	v_cvt_f32_fp8_sdwa v12, v70 src0_sel:BYTE_3
	v_cvt_f32_fp8_sdwa v30, v71 src0_sel:BYTE_3
	v_cvt_f32_fp8_sdwa v13, v72 src0_sel:BYTE_3
	v_cvt_f32_fp8_sdwa v31, v73 src0_sel:BYTE_3
	v_cvt_f32_fp8_sdwa v14, v74 src0_sel:BYTE_3
	v_cvt_f32_fp8_sdwa v32, v75 src0_sel:BYTE_3
	v_cvt_f32_fp8_sdwa v15, v76 src0_sel:BYTE_3
	v_cvt_f32_fp8_sdwa v33, v77 src0_sel:BYTE_3
	v_cvt_f32_fp8_sdwa v16, v78 src0_sel:BYTE_3
	v_cvt_f32_fp8_sdwa v34, v80 src0_sel:BYTE_3
	v_cvt_f32_fp8_sdwa v17, v81 src0_sel:BYTE_3
	v_cvt_f32_fp8_sdwa v35, v79 src0_sel:BYTE_3
	v_pk_mul_f32 v[32:33], v[32:33], s[20:21] op_sel_hi:[1,0]
	v_pk_mul_f32 v[30:31], v[30:31], s[20:21] op_sel_hi:[1,0]
	v_pk_mul_f32 v[18:19], v[16:17], s[20:21] op_sel_hi:[1,0]
	v_pk_mul_f32 v[16:17], v[14:15], s[20:21] op_sel_hi:[1,0]
	v_pk_mul_f32 v[14:15], v[12:13], s[20:21] op_sel_hi:[1,0]
	v_pk_mul_f32 v[12:13], v[10:11], s[20:21] op_sel_hi:[1,0]
	v_pk_mul_f32 v[10:11], v[8:9], s[20:21] op_sel_hi:[1,0]
	v_pk_mul_f32 v[8:9], v[6:7], s[20:21] op_sel_hi:[1,0]
	v_pk_mul_f32 v[6:7], v[4:5], s[20:21] op_sel_hi:[1,0]
	v_pk_mul_f32 v[4:5], v[0:1], s[20:21] op_sel_hi:[1,0]
	v_pk_mul_f32 v[34:35], v[34:35], s[20:21] op_sel_hi:[1,0]
	v_pk_mul_f32 v[28:29], v[28:29], s[20:21] op_sel_hi:[1,0]
	v_pk_mul_f32 v[26:27], v[26:27], s[20:21] op_sel_hi:[1,0]
	v_pk_mul_f32 v[24:25], v[24:25], s[20:21] op_sel_hi:[1,0]
	v_pk_mul_f32 v[22:23], v[22:23], s[20:21] op_sel_hi:[1,0]
	v_pk_mul_f32 v[20:21], v[20:21], s[20:21] op_sel_hi:[1,0]
	global_store_dwordx4 v[40:41], v[82:85], off offset:128
	v_cvt_scalef32_2xpk16_fp6_f32 v[50:55], v[4:19], v[20:35], 1.0
	global_store_dwordx4 v[40:41], v[50:53], off offset:192
	v_mov_b32_e32 v0, v54
	v_mov_b32_e32 v1, v55
	global_store_dwordx4 v[88:89], v[0:3], off offset:192
	s_andn2_b64 exec, exec, s[34:35]
	s_cbranch_execnz .LBB0_566

; __device__ __forceinline__ float bf_lo(unsigned w) { return __uint_as_float(w << 16); }
; __device__ __forceinline__ float bf_hi(unsigned w) { return __uint_as_float(w & 0xffff0000u); }
; __device__ __forceinline__ void fwht64(float (&v)[64]) {
; #pragma unroll
;     for (int s_ = 1; s_ < 64; s_ <<= 1)
; #pragma unroll
;         for (int i = 0; i < 64; ++i) if ((i & s_) == 0) { const float a = v[i], b = v[i | s_]; v[i] = a + b; v[i | s_] = a - b; }
; #pragma unroll
;     for (int i = 0; i < 64; ++i) v[i] *= 0.125f;
; }
; __global__ void __launch_bounds__(NWAVES * 64, 2) fwd(Args args) {
;     ...
;                   for (int j = 0; j < 8; ++j) { const u32x4 w = *(const u32x4*)(AL + (size_t)m * D + lane * 64 + j * 8);
;                       v_[8 * j] = bf_lo(w.x); v_[8 * j + 1] = bf_hi(w.x); v_[8 * j + 2] = bf_lo(w.y); v_[8 * j + 3] = bf_hi(w.y); v_[8 * j + 4] = bf_lo(w.z); v_[8 * j + 5] = bf_hi(w.z); v_[8 * j + 6] = bf_lo(w.w); v_[8 * j + 7] = bf_hi(w.w); }
;                   fwht64(v_);
.LBB0_696:
	v_lshl_add_u64 v[22:23], s[42:43], 0, v[4:5]
	s_mov_b64 s[8:9], 0x20e00000
	v_lshl_add_u64 v[34:35], v[22:23], 0, s[8:9]
	s_mov_b64 s[8:9], 0x20e00040
	v_add_co_u32_e32 v26, vcc, 0x20e00000, v22
	v_lshl_add_u64 v[30:31], v[22:23], 0, s[8:9]
	s_nop 0
	v_addc_co_u32_e32 v27, vcc, 0, v23, vcc
	global_load_dwordx4 v[6:9], v[34:35], off offset:16 nt
	global_load_dwordx4 v[10:13], v[30:31], off offset:32 nt
	global_load_dwordx4 v[14:17], v[34:35], off offset:32 nt
	global_load_dwordx4 v[18:21], v[30:31], off offset:48 nt
	global_load_dwordx4 v[22:25], v[26:27], off offset:64 nt
	s_nop 0
	global_load_dwordx4 v[26:29], v[26:27], off nt
	s_nop 0
	global_load_dwordx4 v[30:33], v[30:31], off offset:16 nt
	s_nop 0
	global_load_dwordx4 v[34:37], v[34:35], off offset:48 nt
	s_mov_b32 s3, 0x54700000
	s_waitcnt vmcnt(0)
	v_lshlrev_b32_e32 v71, 16, v22
	v_lshlrev_b32_e32 v38, 16, v6
	v_and_b32_e32 v6, 0xffff0000, v6
	v_lshlrev_b32_e32 v40, 16, v7
	v_and_b32_e32 v42, 0xffff0000, v7
	v_lshlrev_b32_e32 v44, 16, v8
	v_and_b32_e32 v8, 0xffff0000, v8
	v_lshlrev_b32_e32 v46, 16, v9
	v_and_b32_e32 v48, 0xffff0000, v9
	v_lshlrev_b32_e32 v51, 16, v10
	v_lshlrev_b32_e32 v50, 16, v14
	v_and_b32_e32 v53, 0xffff0000, v10
	v_and_b32_e32 v52, 0xffff0000, v14
	v_lshlrev_b32_e32 v55, 16, v11
	v_lshlrev_b32_e32 v54, 16, v15
	v_and_b32_e32 v11, 0xffff0000, v11
	v_and_b32_e32 v10, 0xffff0000, v15
	v_lshlrev_b32_e32 v15, 16, v12
	v_lshlrev_b32_e32 v14, 16, v16
	v_and_b32_e32 v57, 0xffff0000, v12
	v_and_b32_e32 v56, 0xffff0000, v16
	v_lshlrev_b32_e32 v59, 16, v13
	v_lshlrev_b32_e32 v58, 16, v17
	v_and_b32_e32 v13, 0xffff0000, v13
	v_and_b32_e32 v12, 0xffff0000, v17
	v_lshlrev_b32_e32 v17, 16, v18
	v_and_b32_e32 v61, 0xffff0000, v18
	v_lshlrev_b32_e32 v63, 16, v19
	v_and_b32_e32 v19, 0xffff0000, v19
	v_lshlrev_b32_e32 v65, 16, v20
	v_and_b32_e32 v67, 0xffff0000, v20
	v_lshlrev_b32_e32 v69, 16, v21
	v_and_b32_e32 v21, 0xffff0000, v21
	v_lshlrev_b32_e32 v70, 16, v26
	v_and_b32_e32 v73, 0xffff0000, v22
	v_and_b32_e32 v72, 0xffff0000, v26
	v_lshlrev_b32_e32 v75, 16, v23
	v_lshlrev_b32_e32 v74, 16, v27
	v_and_b32_e32 v23, 0xffff0000, v23
	v_and_b32_e32 v22, 0xffff0000, v27
	v_lshlrev_b32_e32 v27, 16, v24
	v_lshlrev_b32_e32 v26, 16, v28
	v_and_b32_e32 v77, 0xffff0000, v24
	v_and_b32_e32 v76, 0xffff0000, v28
	v_lshlrev_b32_e32 v79, 16, v25
	v_lshlrev_b32_e32 v78, 16, v29
	v_and_b32_e32 v25, 0xffff0000, v25
	v_and_b32_e32 v24, 0xffff0000, v29
	v_lshlrev_b32_e32 v39, 16, v30
	v_and_b32_e32 v7, 0xffff0000, v30
	v_lshlrev_b32_e32 v41, 16, v31
	v_and_b32_e32 v43, 0xffff0000, v31
	v_lshlrev_b32_e32 v45, 16, v32
	v_and_b32_e32 v9, 0xffff0000, v32
	v_lshlrev_b32_e32 v47, 16, v33
	v_and_b32_e32 v49, 0xffff0000, v33
	v_lshlrev_b32_e32 v16, 16, v34
	v_and_b32_e32 v60, 0xffff0000, v34
	v_lshlrev_b32_e32 v62, 16, v35
	v_and_b32_e32 v18, 0xffff0000, v35
	v_lshlrev_b32_e32 v64, 16, v36
	v_and_b32_e32 v66, 0xffff0000, v36
	v_lshlrev_b32_e32 v68, 16, v37
	v_and_b32_e32 v20, 0xffff0000, v37
	v_pk_add_f32 v[28:29], v[70:71], v[72:73]
	v_pk_add_f32 v[30:31], v[74:75], v[22:23]
	v_pk_add_f32 v[32:33], v[26:27], v[76:77]
	v_pk_add_f32 v[34:35], v[78:79], v[24:25]
	v_pk_add_f32 v[36:37], v[38:39], v[6:7]
	v_pk_add_f32 v[80:81], v[40:41], v[42:43]
	v_pk_add_f32 v[82:83], v[44:45], v[8:9]
	v_pk_add_f32 v[88:89], v[54:55], v[10:11]
	v_pk_add_f32 v[90:91], v[14:15], v[56:57]
	v_pk_add_f32 v[92:93], v[58:59], v[12:13]
	v_pk_add_f32 v[94:95], v[16:17], v[60:61]
	v_pk_add_f32 v[96:97], v[62:63], v[18:19]
	v_pk_add_f32 v[100:101], v[68:69], v[20:21]
	v_pk_add_f32 v[70:71], v[70:71], v[72:73] neg_lo:[0,1] neg_hi:[0,1]
	v_pk_add_f32 v[22:23], v[74:75], v[22:23] neg_lo:[0,1] neg_hi:[0,1]
	v_pk_add_f32 v[26:27], v[26:27], v[76:77] neg_lo:[0,1] neg_hi:[0,1]
	v_pk_add_f32 v[24:25], v[78:79], v[24:25] neg_lo:[0,1] neg_hi:[0,1]
	v_pk_add_f32 v[6:7], v[38:39], v[6:7] neg_lo:[0,1] neg_hi:[0,1]
	v_pk_add_f32 v[38:39], v[40:41], v[42:43] neg_lo:[0,1] neg_hi:[0,1]
	v_pk_add_f32 v[8:9], v[44:45], v[8:9] neg_lo:[0,1] neg_hi:[0,1]
	v_pk_add_f32 v[40:41], v[46:47], v[48:49] neg_lo:[0,1] neg_hi:[0,1]
	v_pk_add_f32 v[42:43], v[50:51], v[52:53] neg_lo:[0,1] neg_hi:[0,1]
	v_pk_add_f32 v[10:11], v[54:55], v[10:11] neg_lo:[0,1] neg_hi:[0,1]
	v_pk_add_f32 v[14:15], v[14:15], v[56:57] neg_lo:[0,1] neg_hi:[0,1]
	v_pk_add_f32 v[12:13], v[58:59], v[12:13] neg_lo:[0,1] neg_hi:[0,1]
	v_pk_add_f32 v[16:17], v[16:17], v[60:61] neg_lo:[0,1] neg_hi:[0,1]
	v_pk_add_f32 v[18:19], v[62:63], v[18:19] neg_lo:[0,1] neg_hi:[0,1]
	v_pk_add_f32 v[44:45], v[64:65], v[66:67] neg_lo:[0,1] neg_hi:[0,1]
	v_pk_add_f32 v[20:21], v[68:69], v[20:21] neg_lo:[0,1] neg_hi:[0,1]
	v_pk_add_f32 v[84:85], v[46:47], v[48:49]
	v_pk_add_f32 v[86:87], v[50:51], v[52:53]
	v_pk_add_f32 v[46:47], v[70:71], v[22:23] neg_lo:[0,1] neg_hi:[0,1]
	v_pk_add_f32 v[48:49], v[26:27], v[24:25] neg_lo:[0,1] neg_hi:[0,1]
	v_pk_add_f32 v[50:51], v[6:7], v[38:39] neg_lo:[0,1] neg_hi:[0,1]
	v_pk_add_f32 v[52:53], v[8:9], v[40:41] neg_lo:[0,1] neg_hi:[0,1]
	v_pk_add_f32 v[54:55], v[42:43], v[10:11] neg_lo:[0,1] neg_hi:[0,1]
	v_pk_add_f32 v[56:57], v[14:15], v[12:13] neg_lo:[0,1] neg_hi:[0,1]
	v_pk_add_f32 v[58:59], v[16:17], v[18:19] neg_lo:[0,1] neg_hi:[0,1]
	v_pk_add_f32 v[22:23], v[70:71], v[22:23]
	v_pk_add_f32 v[24:25], v[26:27], v[24:25]
	v_pk_add_f32 v[6:7], v[6:7], v[38:39]
	v_pk_add_f32 v[8:9], v[8:9], v[40:41]
	v_pk_add_f32 v[10:11], v[42:43], v[10:11]
	v_pk_add_f32 v[12:13], v[14:15], v[12:13]
	v_pk_add_f32 v[14:15], v[16:17], v[18:19]
	v_pk_add_f32 v[16:17], v[44:45], v[20:21]
	v_pk_add_f32 v[98:99], v[64:65], v[66:67]
	v_pk_add_f32 v[60:61], v[44:45], v[20:21] neg_lo:[0,1] neg_hi:[0,1]
; __device__ __forceinline__ void fwht64(float (&v)[64]) {
; #pragma unroll
;     for (int s_ = 1; s_ < 64; s_ <<= 1)
; #pragma unroll
;         for (int i = 0; i < 64; ++i) if ((i & s_) == 0) { const float a = v[i], b = v[i | s_]; v[i] = a + b; v[i | s_] = a - b; }
; #pragma unroll
;     for (int i = 0; i < 64; ++i) v[i] *= 0.125f;
; }
	v_pk_add_f32 v[18:19], v[22:23], v[24:25] neg_lo:[0,1] neg_hi:[0,1]
	v_pk_add_f32 v[20:21], v[6:7], v[8:9] neg_lo:[0,1] neg_hi:[0,1]
	v_pk_add_f32 v[26:27], v[10:11], v[12:13] neg_lo:[0,1] neg_hi:[0,1]
	v_pk_add_f32 v[38:39], v[14:15], v[16:17] neg_lo:[0,1] neg_hi:[0,1]
	v_pk_add_f32 v[102:103], v[28:29], v[30:31] neg_lo:[0,1] neg_hi:[0,1]
	v_pk_add_f32 v[104:105], v[32:33], v[34:35] neg_lo:[0,1] neg_hi:[0,1]
	v_pk_add_f32 v[106:107], v[36:37], v[80:81] neg_lo:[0,1] neg_hi:[0,1]
	v_pk_add_f32 v[108:109], v[82:83], v[84:85] neg_lo:[0,1] neg_hi:[0,1]
	v_pk_add_f32 v[28:29], v[28:29], v[30:31]
	v_pk_add_f32 v[30:31], v[32:33], v[34:35]
	v_pk_add_f32 v[32:33], v[36:37], v[80:81]
	v_pk_add_f32 v[34:35], v[82:83], v[84:85]
	v_pk_add_f32 v[36:37], v[86:87], v[88:89]
	v_pk_add_f32 v[80:81], v[90:91], v[92:93]
	v_pk_add_f32 v[82:83], v[94:95], v[96:97]
	v_pk_add_f32 v[84:85], v[98:99], v[100:101]
	v_pk_add_f32 v[40:41], v[18:19], v[20:21] neg_lo:[0,1] neg_hi:[0,1]
	v_pk_add_f32 v[18:19], v[18:19], v[20:21]
	v_pk_add_f32 v[20:21], v[26:27], v[38:39]
	v_pk_add_f32 v[110:111], v[86:87], v[88:89] neg_lo:[0,1] neg_hi:[0,1]
	v_pk_add_f32 v[112:113], v[90:91], v[92:93] neg_lo:[0,1] neg_hi:[0,1]
	v_pk_add_f32 v[114:115], v[94:95], v[96:97] neg_lo:[0,1] neg_hi:[0,1]
	v_pk_add_f32 v[116:117], v[98:99], v[100:101] neg_lo:[0,1] neg_hi:[0,1]
	v_pk_add_f32 v[86:87], v[28:29], v[30:31] neg_lo:[0,1] neg_hi:[0,1]
	v_pk_add_f32 v[88:89], v[32:33], v[34:35] neg_lo:[0,1] neg_hi:[0,1]
	v_pk_add_f32 v[28:29], v[28:29], v[30:31]
	v_pk_add_f32 v[30:31], v[32:33], v[34:35]
	v_pk_add_f32 v[32:33], v[36:37], v[80:81]
	v_pk_add_f32 v[34:35], v[82:83], v[84:85]
	v_pk_add_f32 v[42:43], v[26:27], v[38:39] neg_lo:[0,1] neg_hi:[0,1]
	v_pk_add_f32 v[26:27], v[18:19], v[20:21]
	v_pk_add_f32 v[18:19], v[18:19], v[20:21] neg_lo:[0,1] neg_hi:[0,1]
	v_pk_add_f32 v[20:21], v[22:23], v[24:25]
	v_pk_add_f32 v[6:7], v[6:7], v[8:9]
	v_pk_add_f32 v[8:9], v[10:11], v[12:13]
	v_pk_add_f32 v[10:11], v[14:15], v[16:17]
	v_pk_add_f32 v[118:119], v[102:103], v[104:105] neg_lo:[0,1] neg_hi:[0,1]
	v_pk_add_f32 v[120:121], v[106:107], v[108:109] neg_lo:[0,1] neg_hi:[0,1]
	v_pk_add_f32 v[102:103], v[102:103], v[104:105]
	v_pk_add_f32 v[104:105], v[106:107], v[108:109]
	v_pk_add_f32 v[106:107], v[110:111], v[112:113]
	v_pk_add_f32 v[108:109], v[114:115], v[116:117]
	v_pk_add_f32 v[90:91], v[36:37], v[80:81] neg_lo:[0,1] neg_hi:[0,1]
	v_pk_add_f32 v[36:37], v[28:29], v[30:31] neg_lo:[0,1] neg_hi:[0,1]
	v_pk_add_f32 v[28:29], v[28:29], v[30:31]
	v_pk_add_f32 v[30:31], v[32:33], v[34:35]
	v_pk_add_f32 v[62:63], v[46:47], v[48:49] neg_lo:[0,1] neg_hi:[0,1]
	v_pk_add_f32 v[64:65], v[50:51], v[52:53] neg_lo:[0,1] neg_hi:[0,1]
	v_pk_add_f32 v[66:67], v[54:55], v[56:57] neg_lo:[0,1] neg_hi:[0,1]
	v_pk_add_f32 v[68:69], v[58:59], v[60:61] neg_lo:[0,1] neg_hi:[0,1]
	v_pk_add_f32 v[46:47], v[46:47], v[48:49]
	v_pk_add_f32 v[48:49], v[50:51], v[52:53]
	v_pk_add_f32 v[50:51], v[54:55], v[56:57]
	v_pk_add_f32 v[52:53], v[58:59], v[60:61]
	v_pk_add_f32 v[12:13], v[20:21], v[6:7] neg_lo:[0,1] neg_hi:[0,1]
	v_pk_add_f32 v[14:15], v[8:9], v[10:11] neg_lo:[0,1] neg_hi:[0,1]
	v_pk_add_f32 v[6:7], v[20:21], v[6:7]
	v_pk_add_f32 v[8:9], v[8:9], v[10:11]
	v_pk_add_f32 v[122:123], v[110:111], v[112:113] neg_lo:[0,1] neg_hi:[0,1]
	v_pk_add_f32 v[110:111], v[102:103], v[104:105] neg_lo:[0,1] neg_hi:[0,1]
	v_pk_add_f32 v[102:103], v[102:103], v[104:105]
	v_pk_add_f32 v[104:105], v[106:107], v[108:109]
	v_pk_add_f32 v[92:93], v[82:83], v[84:85] neg_lo:[0,1] neg_hi:[0,1]
	v_pk_add_f32 v[80:81], v[32:33], v[34:35] neg_lo:[0,1] neg_hi:[0,1]
	v_pk_add_f32 v[32:33], v[28:29], v[30:31]
	v_pk_add_f32 v[72:73], v[62:63], v[64:65] neg_lo:[0,1] neg_hi:[0,1]
	v_pk_add_f32 v[74:75], v[66:67], v[68:69] neg_lo:[0,1] neg_hi:[0,1]
	v_pk_add_f32 v[54:55], v[46:47], v[48:49] neg_lo:[0,1] neg_hi:[0,1]
	v_pk_add_f32 v[46:47], v[46:47], v[48:49]
	v_pk_add_f32 v[48:49], v[50:51], v[52:53]
	v_pk_add_f32 v[10:11], v[6:7], v[8:9]
	v_pk_add_f32 v[124:125], v[114:115], v[116:117] neg_lo:[0,1] neg_hi:[0,1]
	v_pk_add_f32 v[112:113], v[106:107], v[108:109] neg_lo:[0,1] neg_hi:[0,1]
	v_pk_add_f32 v[106:107], v[102:103], v[104:105]
	v_pk_add_f32 v[94:95], v[86:87], v[88:89] neg_lo:[0,1] neg_hi:[0,1]
	v_pk_add_f32 v[86:87], v[86:87], v[88:89]
	v_pk_add_f32 v[88:89], v[90:91], v[92:93]
	v_pk_add_f32 v[56:57], v[50:51], v[52:53] neg_lo:[0,1] neg_hi:[0,1]
	v_pk_add_f32 v[50:51], v[46:47], v[48:49]
	v_pk_add_f32 v[22:23], v[72:73], v[74:75] neg_lo:[0,1] neg_hi:[0,1]
	v_add_f32_e32 v2, v32, v33
	v_add_f32_e32 v25, v10, v11
	v_pk_add_f32 v[126:127], v[118:119], v[120:121] neg_lo:[0,1] neg_hi:[0,1]
	v_pk_add_f32 v[118:119], v[118:119], v[120:121]
	v_pk_add_f32 v[120:121], v[122:123], v[124:125]
	v_pk_add_f32 v[96:97], v[90:91], v[92:93] neg_lo:[0,1] neg_hi:[0,1]
	v_pk_add_f32 v[90:91], v[86:87], v[88:89]
	v_pk_add_f32 v[62:63], v[62:63], v[64:65]
	v_pk_add_f32 v[64:65], v[66:67], v[68:69]
	v_sub_f32_e32 v24, v32, v33
	v_sub_f32_e32 v10, v10, v11
	v_add_f32_e32 v11, v106, v107
	v_add_f32_e32 v33, v50, v51
	v_add_f32_e32 v69, v22, v23
	v_sub_f32_e32 v22, v22, v23
	v_mul_f32_e32 v23, 0x3e000000, v2
	v_mul_f32_e32 v25, 0x3e000000, v25
	v_pk_add_f32 v[128:129], v[122:123], v[124:125] neg_lo:[0,1] neg_hi:[0,1]
	v_pk_add_f32 v[122:123], v[118:119], v[120:121]
	v_pk_add_f32 v[66:67], v[62:63], v[64:65]
	v_pk_add_f32 v[6:7], v[6:7], v[8:9] neg_lo:[0,1] neg_hi:[0,1]
	v_pk_add_f32 v[8:9], v[12:13], v[14:15]
	v_pk_add_f32 v[12:13], v[12:13], v[14:15] neg_lo:[0,1] neg_hi:[0,1]
	v_pk_add_f32 v[14:15], v[40:41], v[42:43]
	v_pk_add_f32 v[16:17], v[40:41], v[42:43] neg_lo:[0,1] neg_hi:[0,1]
; __device__ __forceinline__ void fwht64(float (&v)[64]) {
; #pragma unroll
;     for (int s_ = 1; s_ < 64; s_ <<= 1)
; #pragma unroll
;         for (int i = 0; i < 64; ++i) if ((i & s_) == 0) { const float a = v[i], b = v[i | s_]; v[i] = a + b; v[i | s_] = a - b; }
; #pragma unroll
;     for (int i = 0; i < 64; ++i) v[i] *= 0.125f;
; }
; __global__ void __launch_bounds__(NWAVES * 64, 2) fwd(Args args) {
;     ...
;                   float mx = 0.f;
; #pragma unroll
;                   for (int i = 0; i < 64; ++i) mx = fmaxf(mx, fabsf(v_[i]));
;                   mx = wave_max(mx);
	v_add_f32_e32 v39, v90, v91
	v_add_f32_e32 v41, v26, v27
	v_mul_f32_e32 v11, 0x3e000000, v11
	v_mul_f32_e32 v33, 0x3e000000, v33
	v_max3_f32 v2, |v23|, 0, |v25|
	v_pk_add_f32 v[28:29], v[28:29], v[30:31] neg_lo:[0,1] neg_hi:[0,1]
	v_pk_add_f32 v[30:31], v[36:37], v[80:81]
	v_sub_f32_e32 v26, v26, v27
	v_add_f32_e32 v27, v122, v123
	v_add_f32_e32 v43, v66, v67
	v_mul_f32_e32 v39, 0x3e000000, v39
	v_mul_f32_e32 v41, 0x3e000000, v41
	v_max3_f32 v2, v2, |v11|, |v33|
	v_pk_add_f32 v[102:103], v[102:103], v[104:105] neg_lo:[0,1] neg_hi:[0,1]
	v_pk_add_f32 v[104:105], v[110:111], v[112:113]
	v_pk_add_f32 v[46:47], v[46:47], v[48:49] neg_lo:[0,1] neg_hi:[0,1]
	v_pk_add_f32 v[48:49], v[54:55], v[56:57]
	v_add_f32_e32 v45, v30, v31
	v_sub_f32_e32 v30, v30, v31
	v_add_f32_e32 v31, v8, v9
	v_mul_f32_e32 v27, 0x3e000000, v27
	v_mul_f32_e32 v43, 0x3e000000, v43
	v_max3_f32 v2, v2, |v39|, |v41|
	v_pk_add_f32 v[34:35], v[36:37], v[80:81] neg_lo:[0,1] neg_hi:[0,1]
	v_pk_add_f32 v[36:37], v[94:95], v[96:97]
	v_sub_f32_e32 v38, v50, v51
	v_sub_f32_e32 v8, v8, v9
	v_add_f32_e32 v9, v104, v105
	v_add_f32_e32 v51, v48, v49
	v_mul_f32_e32 v45, 0x3e000000, v45
	v_mul_f32_e32 v31, 0x3e000000, v31
	v_max3_f32 v2, v2, |v27|, |v43|
	v_pk_add_f32 v[82:83], v[126:127], v[128:129]
	v_pk_add_f32 v[20:21], v[72:73], v[74:75]
	v_sub_f32_e32 v48, v48, v49
	v_add_f32_e32 v49, v36, v37
	v_sub_f32_e32 v36, v36, v37
	v_add_f32_e32 v37, v14, v15
	v_mul_f32_e32 v70, 0x3e000000, v9
	v_mul_f32_e32 v51, 0x3e000000, v51
	v_max3_f32 v2, v2, |v45|, |v31|
	v_pk_add_f32 v[52:53], v[54:55], v[56:57] neg_lo:[0,1] neg_hi:[0,1]
	v_sub_f32_e32 v14, v14, v15
	v_add_f32_e32 v15, v82, v83
	v_add_f32_e32 v55, v20, v21
	v_mul_f32_e32 v49, 0x3e000000, v49
	v_mul_f32_e32 v37, 0x3e000000, v37
	v_max3_f32 v2, v2, |v70|, |v51|
	v_sub_f32_e32 v20, v20, v21
	v_add_f32_e32 v21, v28, v29
	v_sub_f32_e32 v28, v28, v29
	v_add_f32_e32 v29, v6, v7
	v_mul_f32_e32 v15, 0x3e000000, v15
	v_mul_f32_e32 v55, 0x3e000000, v55
	v_max3_f32 v2, v2, |v49|, |v37|
	v_pk_add_f32 v[86:87], v[86:87], v[88:89] neg_lo:[0,1] neg_hi:[0,1]
	v_sub_f32_e32 v6, v6, v7
	v_add_f32_e32 v7, v102, v103
	v_add_f32_e32 v57, v46, v47
	v_mul_f32_e32 v21, 0x3e000000, v21
	v_mul_f32_e32 v29, 0x3e000000, v29
	v_max3_f32 v2, v2, |v15|, |v55|
	v_pk_add_f32 v[118:119], v[118:119], v[120:121] neg_lo:[0,1] neg_hi:[0,1]
	v_pk_add_f32 v[62:63], v[62:63], v[64:65] neg_lo:[0,1] neg_hi:[0,1]
	v_sub_f32_e32 v46, v46, v47
	v_add_f32_e32 v47, v86, v87
	v_add_f32_e32 v59, v18, v19
	v_mul_f32_e32 v71, 0x3e000000, v7
	v_mul_f32_e32 v57, 0x3e000000, v57
	v_max3_f32 v2, v2, |v21|, |v29|
	v_sub_f32_e32 v18, v18, v19
	v_add_f32_e32 v19, v118, v119
	v_add_f32_e32 v61, v62, v63
	v_mul_f32_e32 v47, 0x3e000000, v47
	v_mul_f32_e32 v59, 0x3e000000, v59
	v_max3_f32 v2, v2, |v71|, |v57|
	v_pk_add_f32 v[108:109], v[110:111], v[112:113] neg_lo:[0,1] neg_hi:[0,1]
	v_sub_f32_e32 v62, v62, v63
	v_add_f32_e32 v63, v34, v35
	v_sub_f32_e32 v34, v34, v35
	v_add_f32_e32 v35, v12, v13
	v_mul_f32_e32 v19, 0x3e000000, v19
	v_mul_f32_e32 v61, 0x3e000000, v61
	v_max3_f32 v2, v2, |v47|, |v59|
	v_pk_add_f32 v[80:81], v[94:95], v[96:97] neg_lo:[0,1] neg_hi:[0,1]
	v_sub_f32_e32 v12, v12, v13
	v_add_f32_e32 v13, v108, v109
	v_add_f32_e32 v65, v52, v53
	v_mul_f32_e32 v63, 0x3e000000, v63
	v_mul_f32_e32 v35, 0x3e000000, v35
	v_max3_f32 v2, v2, |v19|, |v61|
	v_pk_add_f32 v[84:85], v[126:127], v[128:129] neg_lo:[0,1] neg_hi:[0,1]
	v_sub_f32_e32 v44, v66, v67
	v_sub_f32_e32 v52, v52, v53
	v_add_f32_e32 v53, v80, v81
	v_add_f32_e32 v67, v16, v17
	v_mul_f32_e32 v13, 0x3e000000, v13
	v_mul_f32_e32 v65, 0x3e000000, v65
	v_max3_f32 v2, v2, |v63|, |v35|
	v_sub_f32_e32 v16, v16, v17
	v_add_f32_e32 v17, v84, v85
	v_mul_f32_e32 v53, 0x3e000000, v53
	v_mul_f32_e32 v67, 0x3e000000, v67
	v_max3_f32 v2, v2, |v13|, |v65|
	v_mul_f32_e32 v17, 0x3e000000, v17
	v_mul_f32_e32 v69, 0x3e000000, v69
	v_max3_f32 v2, v2, |v53|, |v67|
	v_sub_f32_e32 v32, v106, v107
	v_mul_f32_e32 v24, 0x3e000000, v24
	v_mul_f32_e32 v72, 0x3e000000, v10
	v_max3_f32 v2, v2, |v17|, |v69|
	v_sub_f32_e32 v40, v90, v91
	v_mul_f32_e32 v32, 0x3e000000, v32
	v_mul_f32_e32 v38, 0x3e000000, v38
	v_max3_f32 v2, v2, |v24|, |v72|
	v_sub_f32_e32 v42, v122, v123
	v_mul_f32_e32 v40, 0x3e000000, v40
	v_mul_f32_e32 v26, 0x3e000000, v26
	v_max3_f32 v2, v2, |v32|, |v38|
	v_mul_f32_e32 v42, 0x3e000000, v42
	v_mul_f32_e32 v44, 0x3e000000, v44
	v_max3_f32 v2, v2, |v40|, |v26|
	v_sub_f32_e32 v50, v104, v105
	v_mul_f32_e32 v30, 0x3e000000, v30
	v_mul_f32_e32 v73, 0x3e000000, v8
	v_max3_f32 v2, v2, |v42|, |v44|
	v_mul_f32_e32 v50, 0x3e000000, v50
	v_mul_f32_e32 v48, 0x3e000000, v48
	v_max3_f32 v2, v2, |v30|, |v73|
	v_sub_f32_e32 v54, v82, v83
	v_mul_f32_e32 v36, 0x3e000000, v36
	v_mul_f32_e32 v14, 0x3e000000, v14
	v_max3_f32 v2, v2, |v50|, |v48|
	v_mul_f32_e32 v54, 0x3e000000, v54
	v_mul_f32_e32 v20, 0x3e000000, v20
	v_max3_f32 v2, v2, |v36|, |v14|
	v_sub_f32_e32 v56, v102, v103
	v_mul_f32_e32 v28, 0x3e000000, v28
	v_mul_f32_e32 v74, 0x3e000000, v6
	v_max3_f32 v2, v2, |v54|, |v20|
	v_sub_f32_e32 v58, v86, v87
	v_mul_f32_e32 v56, 0x3e000000, v56
	v_mul_f32_e32 v46, 0x3e000000, v46
	v_max3_f32 v2, v2, |v28|, |v74|
	v_sub_f32_e32 v60, v118, v119
	v_mul_f32_e32 v58, 0x3e000000, v58
	v_mul_f32_e32 v18, 0x3e000000, v18
	v_max3_f32 v2, v2, |v56|, |v46|
	v_mul_f32_e32 v60, 0x3e000000, v60
	v_mul_f32_e32 v62, 0x3e000000, v62
	v_max3_f32 v2, v2, |v58|, |v18|
	v_sub_f32_e32 v64, v108, v109
	v_mul_f32_e32 v34, 0x3e000000, v34
	v_mul_f32_e32 v12, 0x3e000000, v12
	v_max3_f32 v2, v2, |v60|, |v62|
	v_sub_f32_e32 v66, v80, v81
	v_mul_f32_e32 v64, 0x3e000000, v64
	v_mul_f32_e32 v52, 0x3e000000, v52
	v_max3_f32 v2, v2, |v34|, |v12|
	v_sub_f32_e32 v68, v84, v85
	v_mul_f32_e32 v66, 0x3e000000, v66
	v_mul_f32_e32 v16, 0x3e000000, v16
	v_max3_f32 v2, v2, |v64|, |v52|
	v_mul_f32_e32 v68, 0x3e000000, v68
	v_mul_f32_e32 v22, 0x3e000000, v22
	v_max3_f32 v2, v2, |v66|, |v16|
	v_max3_f32 v2, v2, |v68|, |v22|
	ds_swizzle_b32 v6, v2 offset:swizzle(SWAP,1)
	s_waitcnt lgkmcnt(0)
; __device__ __forceinline__ float wave_max(float v) {
;     v = fmaxf(v, __builtin_bit_cast(float, __builtin_amdgcn_ds_swizzle(__builtin_bit_cast(int, v), (1 << 10) | 0x1f)));
;     v = fmaxf(v, __builtin_bit_cast(float, __builtin_amdgcn_ds_swizzle(__builtin_bit_cast(int, v), (2 << 10) | 0x1f)));
;     v = fmaxf(v, __builtin_bit_cast(float, __builtin_amdgcn_ds_swizzle(__builtin_bit_cast(int, v), (4 << 10) | 0x1f)));
;     v = fmaxf(v, __builtin_bit_cast(float, __builtin_amdgcn_ds_swizzle(__builtin_bit_cast(int, v), (8 << 10) | 0x1f)));
;     v = fmaxf(v, __builtin_bit_cast(float, __builtin_amdgcn_ds_swizzle(__builtin_bit_cast(int, v), (16 << 10) | 0x1f)));
;     { const auto rr = __builtin_amdgcn_permlane32_swap(__float_as_uint(v), __float_as_uint(v), false, false); v = fmaxf(__uint_as_float(rr[0]), __uint_as_float(rr[1])); }
;     return v;
; }
; __global__ void __launch_bounds__(NWAVES * 64, 2) fwd(Args args) {
;     ...
;                   mx = wave_max(mx);
;                   const float qs = mx > 0.f ? 127.0f / mx : 1.0f;
; #pragma unroll
;                   for (int j = 0; j < 4; ++j) *(u32x4*)(A8 + (size_t)m * D + lane * 64 + j * 16) =
;                       (u32x4){pk4_i8(v_[16 * j], v_[16 * j + 1], v_[16 * j + 2], v_[16 * j + 3], qs), pk4_i8(v_[16 * j + 4], v_[16 * j + 5], v_[16 * j + 6], v_[16 * j + 7], qs),
;                               pk4_i8(v_[16 * j + 8], v_[16 * j + 9], v_[16 * j + 10], v_[16 * j + 11], qs), pk4_i8(v_[16 * j + 12], v_[16 * j + 13], v_[16 * j + 14], v_[16 * j + 15], qs)};
	v_max_f32_e32 v6, v6, v6
	v_max_f32_e32 v2, v2, v6
	ds_swizzle_b32 v6, v2 offset:swizzle(SWAP,2)
	s_waitcnt lgkmcnt(0)
	v_max_f32_e32 v6, v6, v6
	v_max_f32_e32 v2, v2, v6
	ds_swizzle_b32 v6, v2 offset:swizzle(SWAP,4)
	s_waitcnt lgkmcnt(0)
	v_max_f32_e32 v6, v6, v6
	v_max_f32_e32 v2, v2, v6
	ds_swizzle_b32 v6, v2 offset:swizzle(SWAP,8)
	s_waitcnt lgkmcnt(0)
	v_max_f32_e32 v6, v6, v6
	v_max_f32_e32 v2, v2, v6
	ds_swizzle_b32 v6, v2 offset:swizzle(SWAP,16)
	s_waitcnt lgkmcnt(0)
	v_max_f32_e32 v6, v6, v6
	v_max_f32_e32 v2, v2, v6
	v_mov_b32_e32 v6, v2
	s_nop 1
	v_permlane32_swap_b32_e32 v2, v6
	v_max_f32_e32 v6, v6, v6
	v_max_f32_e32 v2, v2, v2
	v_max_f32_e32 v2, v2, v6
	v_div_scale_f32 v6, s[8:9], v2, v2, s7
	v_rcp_f32_e32 v7, v6
	s_nop 0
	v_fma_f32 v8, -v6, v7, 1.0
	v_fmac_f32_e32 v7, v8, v7
	v_div_scale_f32 v8, vcc, s7, v2, s7
	v_mul_f32_e32 v9, v8, v7
	v_fma_f32 v10, -v6, v9, v8
	v_fmac_f32_e32 v9, v10, v7
	v_fma_f32 v6, -v6, v9, v8
	v_div_fmas_f32 v6, v6, v7, v9
	v_div_fixup_f32 v6, v6, v2, s7
	v_cmp_lt_f32_e32 vcc, 0, v2
	s_nop 1
	v_cndmask_b32_e32 v2, 1.0, v6, vcc
	v_mul_f32_e32 v9, v2, v25
	v_mul_f32_e32 v8, v2, v23
	v_med3_f32 v9, v9, s18, v224
	v_mul_f32_e32 v10, v2, v11
	v_mul_f32_e32 v11, v2, v33
	v_med3_f32 v8, v8, s18, v224
	v_rndne_f32_e32 v9, v9
	v_med3_f32 v10, v10, s18, v224
	v_med3_f32 v11, v11, s18, v224
	v_rndne_f32_e32 v8, v8
	v_cvt_i32_f32_e32 v9, v9
	v_rndne_f32_e32 v10, v10
	v_rndne_f32_e32 v11, v11
	v_cvt_i32_f32_e32 v8, v8
	v_cvt_i32_f32_sdwa v10, v10 dst_sel:WORD_1 dst_unused:UNUSED_PAD src0_sel:DWORD
	v_cvt_i32_f32_e32 v11, v11
	v_lshlrev_b32_e32 v9, 8, v9
	v_and_b32_e32 v9, 0xff00, v9
	v_and_b32_e32 v10, 0xff0000, v10
	v_perm_b32 v8, v11, v8, s19
	v_or3_b32 v8, v8, v9, v10
	v_mul_f32_e32 v10, v2, v41
	v_mul_f32_e32 v9, v2, v39
	v_med3_f32 v10, v10, s18, v224
	v_mul_f32_e32 v11, v2, v27
	v_mul_f32_e32 v23, v2, v43
	v_med3_f32 v9, v9, s18, v224
	v_rndne_f32_e32 v10, v10
	v_med3_f32 v11, v11, s18, v224
	v_med3_f32 v23, v23, s18, v224
	v_rndne_f32_e32 v9, v9
	v_cvt_i32_f32_e32 v10, v10
	v_rndne_f32_e32 v11, v11
	v_rndne_f32_e32 v23, v23
	v_cvt_i32_f32_e32 v9, v9
	v_cvt_i32_f32_sdwa v11, v11 dst_sel:WORD_1 dst_unused:UNUSED_PAD src0_sel:DWORD
	v_cvt_i32_f32_e32 v23, v23
	v_lshlrev_b32_e32 v10, 8, v10
	v_and_b32_e32 v10, 0xff00, v10
	v_and_b32_e32 v11, 0xff0000, v11
	v_perm_b32 v9, v23, v9, s19
	v_or3_b32 v9, v9, v10, v11
	v_mul_f32_e32 v11, v2, v31
	v_mul_f32_e32 v10, v2, v45
	v_med3_f32 v11, v11, s18, v224
	v_mul_f32_e32 v23, v2, v70
	v_mul_f32_e32 v25, v2, v51
	v_med3_f32 v10, v10, s18, v224
	v_rndne_f32_e32 v11, v11
	v_med3_f32 v23, v23, s18, v224
	v_med3_f32 v25, v25, s18, v224
	v_rndne_f32_e32 v10, v10
	v_cvt_i32_f32_e32 v11, v11
	v_rndne_f32_e32 v23, v23
	v_rndne_f32_e32 v25, v25
	v_cvt_i32_f32_e32 v10, v10
	v_cvt_i32_f32_sdwa v23, v23 dst_sel:WORD_1 dst_unused:UNUSED_PAD src0_sel:DWORD
	v_cvt_i32_f32_e32 v25, v25
	v_lshlrev_b32_e32 v11, 8, v11
	v_and_b32_e32 v11, 0xff00, v11
	v_and_b32_e32 v23, 0xff0000, v23
	v_perm_b32 v10, v25, v10, s19
	v_or3_b32 v10, v10, v11, v23
	v_mul_f32_e32 v23, v2, v37
	v_mul_f32_e32 v11, v2, v49
	v_med3_f32 v23, v23, s18, v224
	v_mul_f32_e32 v15, v2, v15
	v_mul_f32_e32 v25, v2, v55
	v_med3_f32 v11, v11, s18, v224
	v_rndne_f32_e32 v23, v23
	v_med3_f32 v15, v15, s18, v224
	v_med3_f32 v25, v25, s18, v224
	v_rndne_f32_e32 v11, v11
	v_cvt_i32_f32_e32 v23, v23
	v_rndne_f32_e32 v15, v15
	v_rndne_f32_e32 v25, v25
	v_cvt_i32_f32_e32 v11, v11
	v_cvt_i32_f32_sdwa v15, v15 dst_sel:WORD_1 dst_unused:UNUSED_PAD src0_sel:DWORD
	v_cvt_i32_f32_e32 v25, v25
	v_lshl_add_u64 v[6:7], s[42:43], 0, v[0:1]
	v_lshlrev_b32_e32 v23, 8, v23
	v_and_b32_e32 v23, 0xff00, v23
	v_and_b32_e32 v15, 0xff0000, v15
	v_perm_b32 v11, v25, v11, s19
	v_add_co_u32_e32 v6, vcc, s3, v6
	v_or3_b32 v11, v11, v23, v15
	s_nop 0
	v_addc_co_u32_e32 v7, vcc, 0, v7, vcc
	global_store_dwordx4 v[6:7], v[8:11], off
	v_mul_f32_e32 v15, v2, v61
	v_med3_f32 v15, v15, s18, v224
	v_mul_f32_e32 v9, v2, v29
	v_mul_f32_e32 v8, v2, v21
	v_med3_f32 v9, v9, s18, v224
	v_mul_f32_e32 v10, v2, v71
	v_mul_f32_e32 v11, v2, v57
	v_med3_f32 v8, v8, s18, v224
	v_rndne_f32_e32 v9, v9
	v_med3_f32 v10, v10, s18, v224
	v_med3_f32 v11, v11, s18, v224
	v_rndne_f32_e32 v8, v8
	v_cvt_i32_f32_e32 v9, v9
	v_rndne_f32_e32 v10, v10
	v_rndne_f32_e32 v11, v11
	v_cvt_i32_f32_e32 v8, v8
	v_cvt_i32_f32_sdwa v10, v10 dst_sel:WORD_1 dst_unused:UNUSED_PAD src0_sel:DWORD
	v_cvt_i32_f32_e32 v11, v11
	v_lshlrev_b32_e32 v9, 8, v9
	v_and_b32_e32 v9, 0xff00, v9
	v_and_b32_e32 v10, 0xff0000, v10
	v_perm_b32 v8, v11, v8, s19
	v_or3_b32 v8, v8, v9, v10
	v_mul_f32_e32 v10, v2, v59
	v_mul_f32_e32 v9, v2, v47
	v_med3_f32 v10, v10, s18, v224
	v_mul_f32_e32 v11, v2, v19
	v_med3_f32 v9, v9, s18, v224
	v_rndne_f32_e32 v10, v10
	v_med3_f32 v11, v11, s18, v224
	v_rndne_f32_e32 v9, v9
	v_cvt_i32_f32_e32 v10, v10
	v_rndne_f32_e32 v11, v11
	v_rndne_f32_e32 v15, v15
	v_cvt_i32_f32_e32 v9, v9
	v_cvt_i32_f32_sdwa v11, v11 dst_sel:WORD_1 dst_unused:UNUSED_PAD src0_sel:DWORD
	v_cvt_i32_f32_e32 v15, v15
	v_lshlrev_b32_e32 v10, 8, v10
	v_and_b32_e32 v10, 0xff00, v10
	v_and_b32_e32 v11, 0xff0000, v11
	v_perm_b32 v9, v15, v9, s19
	v_or3_b32 v9, v9, v10, v11
	v_mul_f32_e32 v11, v2, v35
	v_mul_f32_e32 v10, v2, v63
	v_med3_f32 v11, v11, s18, v224
	v_mul_f32_e32 v13, v2, v13
	v_mul_f32_e32 v15, v2, v65
	v_med3_f32 v10, v10, s18, v224
	v_rndne_f32_e32 v11, v11
	v_med3_f32 v13, v13, s18, v224
	v_med3_f32 v15, v15, s18, v224
	v_rndne_f32_e32 v10, v10
	v_cvt_i32_f32_e32 v11, v11
	v_rndne_f32_e32 v13, v13
	v_rndne_f32_e32 v15, v15
	v_cvt_i32_f32_e32 v10, v10
	v_cvt_i32_f32_sdwa v13, v13 dst_sel:WORD_1 dst_unused:UNUSED_PAD src0_sel:DWORD
; __global__ void __launch_bounds__(NWAVES * 64, 2) fwd(Args args) {
;     ...
;                   const float qs = mx > 0.f ? 127.0f / mx : 1.0f;
; #pragma unroll
;                   for (int j = 0; j < 4; ++j) *(u32x4*)(A8 + (size_t)m * D + lane * 64 + j * 16) =
;                       (u32x4){pk4_i8(v_[16 * j], v_[16 * j + 1], v_[16 * j + 2], v_[16 * j + 3], qs), pk4_i8(v_[16 * j + 4], v_[16 * j + 5], v_[16 * j + 6], v_[16 * j + 7], qs),
;                               pk4_i8(v_[16 * j + 8], v_[16 * j + 9], v_[16 * j + 10], v_[16 * j + 11], qs), pk4_i8(v_[16 * j + 12], v_[16 * j + 13], v_[16 * j + 14], v_[16 * j + 15], qs)};
;                   if (lane == 0) ROWS[m] = 1.0f / qs;
	v_cvt_i32_f32_e32 v15, v15
	v_lshlrev_b32_e32 v11, 8, v11
	v_and_b32_e32 v11, 0xff00, v11
	v_and_b32_e32 v13, 0xff0000, v13
	v_perm_b32 v10, v15, v10, s19
	v_or3_b32 v10, v10, v11, v13
	v_mul_f32_e32 v13, v2, v67
	v_mul_f32_e32 v11, v2, v53
	v_med3_f32 v13, v13, s18, v224
	v_mul_f32_e32 v15, v2, v17
	v_mul_f32_e32 v17, v2, v69
	v_med3_f32 v11, v11, s18, v224
	v_rndne_f32_e32 v13, v13
	v_med3_f32 v15, v15, s18, v224
	v_med3_f32 v17, v17, s18, v224
	v_rndne_f32_e32 v11, v11
	v_cvt_i32_f32_e32 v13, v13
	v_rndne_f32_e32 v15, v15
	v_rndne_f32_e32 v17, v17
	v_cvt_i32_f32_e32 v11, v11
	v_cvt_i32_f32_sdwa v15, v15 dst_sel:WORD_1 dst_unused:UNUSED_PAD src0_sel:DWORD
	v_cvt_i32_f32_e32 v17, v17
	v_lshlrev_b32_e32 v13, 8, v13
	v_and_b32_e32 v13, 0xff00, v13
	v_and_b32_e32 v15, 0xff0000, v15
	v_perm_b32 v11, v17, v11, s19
	v_or3_b32 v11, v11, v13, v15
	global_store_dwordx4 v[6:7], v[8:11], off offset:16
	v_mul_f32_e32 v13, v2, v44
	v_med3_f32 v13, v13, s18, v224
	v_mul_f32_e32 v9, v2, v72
	v_mul_f32_e32 v8, v2, v24
	v_med3_f32 v9, v9, s18, v224
	v_mul_f32_e32 v10, v2, v32
	v_mul_f32_e32 v11, v2, v38
	v_med3_f32 v8, v8, s18, v224
	v_rndne_f32_e32 v9, v9
	v_med3_f32 v10, v10, s18, v224
	v_med3_f32 v11, v11, s18, v224
	v_rndne_f32_e32 v8, v8
	v_cvt_i32_f32_e32 v9, v9
	v_rndne_f32_e32 v10, v10
	v_rndne_f32_e32 v11, v11
	v_cvt_i32_f32_e32 v8, v8
	v_cvt_i32_f32_sdwa v10, v10 dst_sel:WORD_1 dst_unused:UNUSED_PAD src0_sel:DWORD
	v_cvt_i32_f32_e32 v11, v11
	v_lshlrev_b32_e32 v9, 8, v9
	v_and_b32_e32 v9, 0xff00, v9
	v_and_b32_e32 v10, 0xff0000, v10
	v_perm_b32 v8, v11, v8, s19
	v_or3_b32 v8, v8, v9, v10
	v_mul_f32_e32 v10, v2, v26
	v_mul_f32_e32 v9, v2, v40
	v_med3_f32 v10, v10, s18, v224
	v_mul_f32_e32 v11, v2, v42
	v_med3_f32 v9, v9, s18, v224
	v_rndne_f32_e32 v10, v10
	v_med3_f32 v11, v11, s18, v224
	v_rndne_f32_e32 v9, v9
	v_cvt_i32_f32_e32 v10, v10
	v_rndne_f32_e32 v11, v11
	v_rndne_f32_e32 v13, v13
	v_cvt_i32_f32_e32 v9, v9
	v_cvt_i32_f32_sdwa v11, v11 dst_sel:WORD_1 dst_unused:UNUSED_PAD src0_sel:DWORD
	v_cvt_i32_f32_e32 v13, v13
	v_lshlrev_b32_e32 v10, 8, v10
	v_and_b32_e32 v10, 0xff00, v10
	v_and_b32_e32 v11, 0xff0000, v11
	v_perm_b32 v9, v13, v9, s19
	v_or3_b32 v9, v9, v10, v11
	v_mul_f32_e32 v11, v2, v73
	v_mul_f32_e32 v10, v2, v30
	v_med3_f32 v11, v11, s18, v224
	v_mul_f32_e32 v13, v2, v50
	v_mul_f32_e32 v15, v2, v48
	v_med3_f32 v10, v10, s18, v224
	v_rndne_f32_e32 v11, v11
	v_med3_f32 v13, v13, s18, v224
	v_med3_f32 v15, v15, s18, v224
	v_rndne_f32_e32 v10, v10
	v_cvt_i32_f32_e32 v11, v11
	v_rndne_f32_e32 v13, v13
	v_rndne_f32_e32 v15, v15
	v_cvt_i32_f32_e32 v10, v10
	v_cvt_i32_f32_sdwa v13, v13 dst_sel:WORD_1 dst_unused:UNUSED_PAD src0_sel:DWORD
	v_cvt_i32_f32_e32 v15, v15
	v_lshlrev_b32_e32 v11, 8, v11
	v_and_b32_e32 v11, 0xff00, v11
	v_and_b32_e32 v13, 0xff0000, v13
	v_perm_b32 v10, v15, v10, s19
	v_or3_b32 v10, v10, v11, v13
	v_mul_f32_e32 v13, v2, v14
	v_mul_f32_e32 v11, v2, v36
	v_med3_f32 v13, v13, s18, v224
	v_mul_f32_e32 v14, v2, v54
	v_mul_f32_e32 v15, v2, v20
	v_med3_f32 v11, v11, s18, v224
	v_rndne_f32_e32 v13, v13
	v_med3_f32 v14, v14, s18, v224
	v_med3_f32 v15, v15, s18, v224
	v_rndne_f32_e32 v11, v11
	v_cvt_i32_f32_e32 v13, v13
	v_rndne_f32_e32 v14, v14
	v_rndne_f32_e32 v15, v15
	v_cvt_i32_f32_e32 v11, v11
	v_cvt_i32_f32_sdwa v14, v14 dst_sel:WORD_1 dst_unused:UNUSED_PAD src0_sel:DWORD
	v_cvt_i32_f32_e32 v15, v15
	v_lshlrev_b32_e32 v13, 8, v13
	v_and_b32_e32 v13, 0xff00, v13
	v_and_b32_e32 v14, 0xff0000, v14
	v_perm_b32 v11, v15, v11, s19
	v_or3_b32 v11, v11, v13, v14
	global_store_dwordx4 v[6:7], v[8:11], off offset:32
	v_mul_f32_e32 v13, v2, v62
	v_med3_f32 v13, v13, s18, v224
	v_mul_f32_e32 v9, v2, v74
	v_mul_f32_e32 v8, v2, v28
	v_med3_f32 v9, v9, s18, v224
	v_mul_f32_e32 v10, v2, v56
	v_mul_f32_e32 v11, v2, v46
	v_med3_f32 v8, v8, s18, v224
	v_rndne_f32_e32 v9, v9
	v_med3_f32 v10, v10, s18, v224
	v_med3_f32 v11, v11, s18, v224
	v_rndne_f32_e32 v8, v8
	v_cvt_i32_f32_e32 v9, v9
	v_rndne_f32_e32 v10, v10
	v_rndne_f32_e32 v11, v11
	v_cvt_i32_f32_e32 v8, v8
	v_cvt_i32_f32_sdwa v10, v10 dst_sel:WORD_1 dst_unused:UNUSED_PAD src0_sel:DWORD
	v_cvt_i32_f32_e32 v11, v11
	v_lshlrev_b32_e32 v9, 8, v9
	v_and_b32_e32 v9, 0xff00, v9
	v_and_b32_e32 v10, 0xff0000, v10
	v_perm_b32 v8, v11, v8, s19
	v_or3_b32 v8, v8, v9, v10
	v_mul_f32_e32 v10, v2, v18
	v_mul_f32_e32 v9, v2, v58
	v_med3_f32 v10, v10, s18, v224
	v_mul_f32_e32 v11, v2, v60
	v_med3_f32 v9, v9, s18, v224
	v_rndne_f32_e32 v10, v10
	v_med3_f32 v11, v11, s18, v224
	v_rndne_f32_e32 v9, v9
	v_cvt_i32_f32_e32 v10, v10
	v_rndne_f32_e32 v11, v11
	v_rndne_f32_e32 v13, v13
	v_cvt_i32_f32_e32 v9, v9
	v_cvt_i32_f32_sdwa v11, v11 dst_sel:WORD_1 dst_unused:UNUSED_PAD src0_sel:DWORD
	v_cvt_i32_f32_e32 v13, v13
	v_lshlrev_b32_e32 v10, 8, v10
	v_and_b32_e32 v10, 0xff00, v10
	v_and_b32_e32 v11, 0xff0000, v11
	v_perm_b32 v9, v13, v9, s19
	v_or3_b32 v9, v9, v10, v11
	v_mul_f32_e32 v11, v2, v12
	v_mul_f32_e32 v10, v2, v34
	v_med3_f32 v11, v11, s18, v224
	v_mul_f32_e32 v12, v2, v64
	v_mul_f32_e32 v13, v2, v52
	v_med3_f32 v10, v10, s18, v224
	v_rndne_f32_e32 v11, v11
	v_med3_f32 v12, v12, s18, v224
	v_med3_f32 v13, v13, s18, v224
	v_rndne_f32_e32 v10, v10
	v_cvt_i32_f32_e32 v11, v11
	v_rndne_f32_e32 v12, v12
	v_rndne_f32_e32 v13, v13
	v_cvt_i32_f32_e32 v10, v10
	v_cvt_i32_f32_sdwa v12, v12 dst_sel:WORD_1 dst_unused:UNUSED_PAD src0_sel:DWORD
	v_cvt_i32_f32_e32 v13, v13
	v_lshlrev_b32_e32 v11, 8, v11
	v_and_b32_e32 v11, 0xff00, v11
	v_and_b32_e32 v12, 0xff0000, v12
	v_perm_b32 v10, v13, v10, s19
	v_or3_b32 v10, v10, v11, v12
	v_mul_f32_e32 v12, v2, v16
	v_mul_f32_e32 v11, v2, v66
	v_med3_f32 v12, v12, s18, v224
	v_mul_f32_e32 v13, v2, v68
	v_mul_f32_e32 v14, v2, v22
	v_med3_f32 v11, v11, s18, v224
	v_rndne_f32_e32 v12, v12
	v_med3_f32 v13, v13, s18, v224
	v_med3_f32 v14, v14, s18, v224
	v_rndne_f32_e32 v11, v11
	v_cvt_i32_f32_e32 v12, v12
	v_rndne_f32_e32 v13, v13
	v_rndne_f32_e32 v14, v14
	v_cvt_i32_f32_e32 v11, v11
	v_cvt_i32_f32_sdwa v13, v13 dst_sel:WORD_1 dst_unused:UNUSED_PAD src0_sel:DWORD
	v_cvt_i32_f32_e32 v14, v14
	v_lshlrev_b32_e32 v12, 8, v12
	v_and_b32_e32 v12, 0xff00, v12
	v_and_b32_e32 v13, 0xff0000, v13
	v_perm_b32 v11, v14, v11, s19
	v_or3_b32 v11, v11, v12, v13
	global_store_dwordx4 v[6:7], v[8:11], off offset:48
	s_and_saveexec_b64 s[44:45], s[36:37]
	s_cbranch_execz .LBB0_695
	v_div_scale_f32 v6, s[8:9], v2, v2, 1.0
	v_rcp_f32_e32 v7, v6
	v_div_scale_f32 v8, vcc, 1.0, v2, 1.0
	s_add_u32 s8, s42, s1
	v_fma_f32 v9, -v6, v7, 1.0
	v_fmac_f32_e32 v7, v9, v7
	v_mul_f32_e32 v9, v8, v7
	v_fma_f32 v10, -v6, v9, v8
	v_fmac_f32_e32 v9, v10, v7
	v_fma_f32 v6, -v6, v9, v8
	v_div_fmas_f32 v6, v6, v7, v9
	v_div_fixup_f32 v2, v6, v2, 1.0
	s_addc_u32 s9, s43, s2
	global_store_dword v3, v2, s[8:9]
	s_branch .LBB0_695

; __device__ __forceinline__ unsigned cvt_pk_bf16(float lo, float hi) { unsigned r; asm volatile("v_cvt_pk_bf16_f32 %0, %1, %2" : "=v"(r) : "v"(lo), "v"(hi)); return r; }
; __device__ __forceinline__ void rms_row_to_bf16(const float* xrow, const float* g, bf16_t* orow, int lane, unsigned char* o8row = nullptr) {
;     const f32x4* xr = (const f32x4*)xrow + lane; const f32x4* gr = (const f32x4*)g + lane;
;     f32x4 v[16]; float s = 0.f;
; #pragma unroll
;     for (int j = 0; j < 16; ++j) { v[j] = xr[64 * j]; s += (v[j].x * v[j].x + v[j].y * v[j].y) + (v[j].z * v[j].z + v[j].w * v[j].w); }
;     const float rstd = 1.0f / sqrtf(wave_sum(s) * (1.f / D) + EPS);
;     u32x2* o8 = (u32x2*)orow + lane;
; #pragma unroll
;     for (int j = 0; j < 16; ++j) { const f32x4 gg = gr[64 * j]; const f32x4 y = v[j] * rstd * gg;
;         if (orow) { u32x2 w; w.x = cvt_pk_bf16(y.x, y.y); w.y = cvt_pk_bf16(y.z, y.w); o8[64 * j] = w; }
;         if (o8row) ((unsigned*)o8row)[lane + 64 * j] = pk4_i8(y.x, y.y, y.z, y.w, XN_QS); }
; }
.LBB0_921:
	global_load_dwordx4 v[64:67], v[94:95], off nt
	global_load_dwordx4 v[60:63], v[94:95], off offset:1024 nt
	global_load_dwordx4 v[56:59], v[94:95], off offset:2048 nt
	global_load_dwordx4 v[52:55], v[94:95], off offset:3072 nt
	s_add_i32 s34, s34, s38
	s_cmpk_lt_i32 s34, 0x2000
	s_waitcnt vmcnt(0)
	v_mul_f32_e32 v2, v65, v65
	v_mul_f32_e32 v4, v67, v67
	v_fmac_f32_e32 v2, v64, v64
	v_fmac_f32_e32 v4, v66, v66
	v_add_f32_e32 v2, v2, v4
	v_mul_f32_e32 v4, v61, v61
	v_mul_f32_e32 v5, v63, v63
	v_fmac_f32_e32 v4, v60, v60
	v_fmac_f32_e32 v5, v62, v62
	v_add_f32_e32 v4, v4, v5
	v_add_f32_e32 v2, v2, v4
	v_mul_f32_e32 v4, v57, v57
	v_mul_f32_e32 v5, v59, v59
	v_fmac_f32_e32 v4, v56, v56
	v_fmac_f32_e32 v5, v58, v58
	v_add_f32_e32 v4, v4, v5
	v_add_f32_e32 v2, v2, v4
	v_mul_f32_e32 v4, v53, v53
	v_mul_f32_e32 v5, v55, v55
	v_fmac_f32_e32 v4, v52, v52
	v_fmac_f32_e32 v5, v54, v54
	v_add_f32_e32 v4, v4, v5
	v_add_f32_e32 v2, v2, v4
	v_add_co_u32_e32 v4, vcc, s1, v94
	s_nop 1
	v_addc_co_u32_e32 v5, vcc, 0, v95, vcc
	v_add_co_u32_e32 v6, vcc, s21, v94
	global_load_dwordx4 v[44:47], v[4:5], off offset:1024
	global_load_dwordx4 v[40:43], v[4:5], off offset:2048
	v_addc_co_u32_e32 v7, vcc, 0, v95, vcc
	global_load_dwordx4 v[48:51], v[6:7], off offset:-4096
	global_load_dwordx4 v[36:39], v[4:5], off offset:3072
	global_load_dwordx4 v[32:35], v[6:7], off
	global_load_dwordx4 v[28:31], v[6:7], off offset:1024
	global_load_dwordx4 v[24:27], v[6:7], off offset:2048
	global_load_dwordx4 v[12:15], v[6:7], off offset:3072
	s_waitcnt vmcnt(5)
	v_mul_f32_e32 v8, v49, v49
	v_mul_f32_e32 v9, v51, v51
	v_fmac_f32_e32 v8, v48, v48
	v_fmac_f32_e32 v9, v50, v50
	v_add_f32_e32 v8, v8, v9
	v_add_f32_e32 v2, v2, v8
	v_mul_f32_e32 v8, v45, v45
	v_mul_f32_e32 v9, v47, v47
	v_fmac_f32_e32 v8, v44, v44
	v_fmac_f32_e32 v9, v46, v46
	v_add_f32_e32 v8, v8, v9
	v_add_f32_e32 v2, v2, v8
	v_mul_f32_e32 v8, v41, v41
	v_mul_f32_e32 v9, v43, v43
	v_fmac_f32_e32 v8, v40, v40
	v_fmac_f32_e32 v9, v42, v42
	s_waitcnt vmcnt(4)
	v_mul_f32_e32 v4, v37, v37
	v_mul_f32_e32 v5, v39, v39
	v_add_f32_e32 v8, v8, v9
	v_fmac_f32_e32 v4, v36, v36
	v_fmac_f32_e32 v5, v38, v38
	v_add_f32_e32 v2, v2, v8
	v_add_f32_e32 v4, v4, v5
	v_add_f32_e32 v2, v2, v4
	s_waitcnt vmcnt(3)
	v_mul_f32_e32 v4, v33, v33
	v_mul_f32_e32 v5, v35, v35
	v_fmac_f32_e32 v4, v32, v32
	v_fmac_f32_e32 v5, v34, v34
	v_add_f32_e32 v4, v4, v5
	v_add_f32_e32 v2, v2, v4
	s_waitcnt vmcnt(2)
	v_mul_f32_e32 v4, v29, v29
	v_mul_f32_e32 v5, v31, v31
	v_fmac_f32_e32 v4, v28, v28
	v_fmac_f32_e32 v5, v30, v30
	v_add_f32_e32 v4, v4, v5
	v_add_f32_e32 v2, v2, v4
	s_waitcnt vmcnt(1)
	v_mul_f32_e32 v4, v25, v25
	v_mul_f32_e32 v5, v27, v27
	v_fmac_f32_e32 v4, v24, v24
	v_fmac_f32_e32 v5, v26, v26
	v_add_f32_e32 v4, v4, v5
	v_add_f32_e32 v2, v2, v4
	s_waitcnt vmcnt(0)
	v_mul_f32_e32 v4, v13, v13
	v_mul_f32_e32 v5, v15, v15
	v_fmac_f32_e32 v4, v12, v12
	v_fmac_f32_e32 v5, v14, v14
	v_add_f32_e32 v4, v4, v5
	v_add_f32_e32 v2, v2, v4
	v_add_co_u32_e32 v4, vcc, s74, v94
	s_nop 1
	v_addc_co_u32_e32 v5, vcc, 0, v95, vcc
	global_load_dwordx4 v[20:23], v[4:5], off
	global_load_dwordx4 v[16:19], v[4:5], off offset:1024
	global_load_dwordx4 v[8:11], v[4:5], off offset:2048
	v_lshl_add_u64 v[94:95], v[94:95], 0, s[30:31]
	s_waitcnt vmcnt(2)
	v_mul_f32_e32 v6, v21, v21
	v_mul_f32_e32 v7, v23, v23
	v_fmac_f32_e32 v6, v20, v20
	v_fmac_f32_e32 v7, v22, v22
	v_add_f32_e32 v6, v6, v7
	v_add_f32_e32 v2, v2, v6
	s_waitcnt vmcnt(1)
	v_mul_f32_e32 v6, v17, v17
	v_mul_f32_e32 v7, v19, v19
	v_fmac_f32_e32 v6, v16, v16
	v_fmac_f32_e32 v7, v18, v18
	v_add_f32_e32 v6, v6, v7
	v_add_f32_e32 v2, v2, v6
	s_waitcnt vmcnt(0)
	v_mul_f32_e32 v6, v9, v9
	v_mul_f32_e32 v7, v11, v11
	v_fmac_f32_e32 v6, v8, v8
	v_fmac_f32_e32 v7, v10, v10
	v_add_f32_e32 v6, v6, v7
	v_add_f32_e32 v2, v2, v6
	global_load_dwordx4 v[4:7], v[4:5], off offset:3072
	s_waitcnt vmcnt(0)
	v_mul_f32_e32 v96, v5, v5
	v_mul_f32_e32 v97, v7, v7
	v_fmac_f32_e32 v96, v4, v4
	v_fmac_f32_e32 v97, v6, v6
	v_add_f32_e32 v96, v96, v97
	v_add_f32_e32 v2, v2, v96
	ds_swizzle_b32 v96, v2 offset:swizzle(SWAP,1)
	s_waitcnt lgkmcnt(0)
	v_add_f32_e32 v2, v2, v96
	ds_swizzle_b32 v96, v2 offset:swizzle(SWAP,2)
	s_waitcnt lgkmcnt(0)
	v_add_f32_e32 v2, v2, v96
	ds_swizzle_b32 v96, v2 offset:swizzle(SWAP,4)
	s_waitcnt lgkmcnt(0)
	v_add_f32_e32 v2, v2, v96
	ds_swizzle_b32 v96, v2 offset:swizzle(SWAP,8)
	s_waitcnt lgkmcnt(0)
	v_add_f32_e32 v2, v2, v96
	ds_swizzle_b32 v96, v2 offset:swizzle(SWAP,16)
	s_waitcnt lgkmcnt(0)
	v_add_f32_e32 v2, v2, v96
	v_mov_b32_e32 v96, v2
	s_nop 1
	v_permlane32_swap_b32_e32 v2, v96
	v_add_f32_e32 v2, v2, v96
	v_fmamk_f32 v2, v2, 0x39800000, v252
	v_cmp_gt_f32_e32 vcc, s27, v2
	v_mul_f32_e32 v96, 0x4f800000, v2
	s_nop 0
	v_cndmask_b32_e32 v2, v2, v96, vcc
	v_sqrt_f32_e32 v96, v2
	s_nop 0
	v_add_u32_e32 v97, -1, v96
	v_fma_f32 v98, -v97, v96, v2
	v_cmp_ge_f32_e64 s[36:37], 0, v98
	v_add_u32_e32 v98, 1, v96
	s_nop 0
	v_cndmask_b32_e64 v97, v96, v97, s[36:37]
	v_fma_f32 v96, -v98, v96, v2
	v_cmp_lt_f32_e64 s[36:37], 0, v96
	s_nop 1
	v_cndmask_b32_e64 v96, v97, v98, s[36:37]
	v_mul_f32_e32 v97, 0x37800000, v96
	v_cndmask_b32_e32 v96, v96, v97, vcc
	v_cmp_class_f32_e32 vcc, v2, v222
	s_nop 1
	v_cndmask_b32_e32 v2, v96, v2, vcc
	v_div_scale_f32 v96, s[2:3], v2, v2, 1.0
	v_rcp_f32_e32 v97, v96
	s_nop 0
	v_fma_f32 v98, -v96, v97, 1.0
	v_fmac_f32_e32 v97, v98, v97
	v_div_scale_f32 v98, vcc, 1.0, v2, 1.0
	v_mul_f32_e32 v99, v98, v97
	v_fma_f32 v100, -v96, v99, v98
	v_fmac_f32_e32 v99, v100, v97
	v_fma_f32 v96, -v96, v99, v98
	v_div_fmas_f32 v96, v96, v97, v99
	v_div_fixup_f32 v2, v96, v2, 1.0
	global_load_dwordx4 v[96:99], v[0:1], off
	v_pk_mul_f32 v[64:65], v[64:65], v[2:3] op_sel_hi:[1,0]
	v_pk_mul_f32 v[66:67], v[66:67], v[2:3] op_sel_hi:[1,0]
	v_pk_mul_f32 v[24:25], v[24:25], v[2:3] op_sel_hi:[1,0]
	v_pk_mul_f32 v[26:27], v[26:27], v[2:3] op_sel_hi:[1,0]
	v_pk_mul_f32 v[20:21], v[20:21], v[2:3] op_sel_hi:[1,0]
	v_pk_mul_f32 v[22:23], v[22:23], v[2:3] op_sel_hi:[1,0]
	v_pk_mul_f32 v[16:17], v[16:17], v[2:3] op_sel_hi:[1,0]
	v_pk_mul_f32 v[18:19], v[18:19], v[2:3] op_sel_hi:[1,0]
	s_waitcnt vmcnt(0)
; __device__ __forceinline__ unsigned cvt_pk_bf16(float lo, float hi) { unsigned r; asm volatile("v_cvt_pk_bf16_f32 %0, %1, %2" : "=v"(r) : "v"(lo), "v"(hi)); return r; }
; __device__ __forceinline__ unsigned pk4_i8(float a, float b, float c, float d, float qs) {
;     const int q0 = (int)__builtin_rintf(fminf(fmaxf(a * qs, -127.f), 127.f)), q1 = (int)__builtin_rintf(fminf(fmaxf(b * qs, -127.f), 127.f));
;     const int q2 = (int)__builtin_rintf(fminf(fmaxf(c * qs, -127.f), 127.f)), q3 = (int)__builtin_rintf(fminf(fmaxf(d * qs, -127.f), 127.f));
;     return ((unsigned)q0 & 0xffu) | (((unsigned)q1 & 0xffu) << 8) | (((unsigned)q2 & 0xffu) << 16) | ((unsigned)q3 << 24);
; }
; __device__ __forceinline__ void rms_row_to_bf16(const float* xrow, const float* g, bf16_t* orow, int lane, unsigned char* o8row = nullptr) {
;     ...
;     for (int j = 0; j < 16; ++j) { const f32x4 gg = gr[64 * j]; const f32x4 y = v[j] * rstd * gg;
;         if (orow) { u32x2 w; w.x = cvt_pk_bf16(y.x, y.y); w.y = cvt_pk_bf16(y.z, y.w); o8[64 * j] = w; }
;         if (o8row) ((unsigned*)o8row)[lane + 64 * j] = pk4_i8(y.x, y.y, y.z, y.w, XN_QS); }
	v_pk_mul_f32 v[64:65], v[96:97], v[64:65]
	v_pk_mul_f32 v[66:67], v[98:99], v[66:67]
	v_mul_f32_e32 v65, 0x41fe0000, v65
	v_mul_f32_e32 v64, 0x41fe0000, v64
	v_med3_f32 v65, v65, s18, v224
	v_mul_f32_e32 v66, 0x41fe0000, v66
	v_mul_f32_e32 v67, 0x41fe0000, v67
	v_med3_f32 v64, v64, s18, v224
	v_rndne_f32_e32 v65, v65
	v_med3_f32 v66, v66, s18, v224
	v_med3_f32 v67, v67, s18, v224
	v_rndne_f32_e32 v64, v64
	v_cvt_i32_f32_e32 v65, v65
	v_rndne_f32_e32 v66, v66
	v_rndne_f32_e32 v67, v67
	v_cvt_i32_f32_e32 v64, v64
	v_cvt_i32_f32_sdwa v66, v66 dst_sel:WORD_1 dst_unused:UNUSED_PAD src0_sel:DWORD
	v_cvt_i32_f32_e32 v67, v67
	v_lshlrev_b32_e32 v65, 8, v65
	v_and_b32_e32 v65, 0xff00, v65
	v_and_b32_e32 v66, 0xff0000, v66
	v_perm_b32 v64, v67, v64, s19
	v_or3_b32 v64, v64, v65, v66
	global_store_dword v[92:93], v64, off
	v_pk_mul_f32 v[64:65], v[60:61], v[2:3] op_sel_hi:[1,0]
	v_pk_mul_f32 v[66:67], v[62:63], v[2:3] op_sel_hi:[1,0]
	global_load_dwordx4 v[60:63], v[0:1], off offset:1024
	s_waitcnt vmcnt(0)
	v_pk_mul_f32 v[60:61], v[60:61], v[64:65]
	v_pk_mul_f32 v[62:63], v[62:63], v[66:67]
	v_mul_f32_e32 v61, 0x41fe0000, v61
	v_mul_f32_e32 v60, 0x41fe0000, v60
	v_med3_f32 v61, v61, s18, v224
	v_mul_f32_e32 v62, 0x41fe0000, v62
	v_mul_f32_e32 v63, 0x41fe0000, v63
	v_med3_f32 v60, v60, s18, v224
	v_rndne_f32_e32 v61, v61
	v_med3_f32 v62, v62, s18, v224
	v_med3_f32 v63, v63, s18, v224
	v_rndne_f32_e32 v60, v60
	v_cvt_i32_f32_e32 v61, v61
	v_rndne_f32_e32 v62, v62
	v_rndne_f32_e32 v63, v63
	v_cvt_i32_f32_e32 v60, v60
	v_cvt_i32_f32_sdwa v62, v62 dst_sel:WORD_1 dst_unused:UNUSED_PAD src0_sel:DWORD
	v_cvt_i32_f32_e32 v63, v63
	v_lshlrev_b32_e32 v61, 8, v61
	v_and_b32_e32 v61, 0xff00, v61
	v_and_b32_e32 v62, 0xff0000, v62
	v_perm_b32 v60, v63, v60, s19
	v_or3_b32 v60, v60, v61, v62
	global_store_dword v[92:93], v60, off offset:256
	v_pk_mul_f32 v[60:61], v[56:57], v[2:3] op_sel_hi:[1,0]
	v_pk_mul_f32 v[62:63], v[58:59], v[2:3] op_sel_hi:[1,0]
	global_load_dwordx4 v[56:59], v[0:1], off offset:2048
	s_waitcnt vmcnt(0)
	v_pk_mul_f32 v[56:57], v[56:57], v[60:61]
	v_pk_mul_f32 v[58:59], v[58:59], v[62:63]
	v_mul_f32_e32 v57, 0x41fe0000, v57
	v_mul_f32_e32 v56, 0x41fe0000, v56
	v_med3_f32 v57, v57, s18, v224
	v_mul_f32_e32 v58, 0x41fe0000, v58
	v_mul_f32_e32 v59, 0x41fe0000, v59
	v_med3_f32 v56, v56, s18, v224
	v_rndne_f32_e32 v57, v57
	v_med3_f32 v58, v58, s18, v224
	v_med3_f32 v59, v59, s18, v224
	v_rndne_f32_e32 v56, v56
	v_cvt_i32_f32_e32 v57, v57
	v_rndne_f32_e32 v58, v58
	v_rndne_f32_e32 v59, v59
	v_cvt_i32_f32_e32 v56, v56
	v_cvt_i32_f32_sdwa v58, v58 dst_sel:WORD_1 dst_unused:UNUSED_PAD src0_sel:DWORD
	v_cvt_i32_f32_e32 v59, v59
	v_lshlrev_b32_e32 v57, 8, v57
	v_and_b32_e32 v57, 0xff00, v57
	v_and_b32_e32 v58, 0xff0000, v58
	v_perm_b32 v56, v59, v56, s19
	v_or3_b32 v56, v56, v57, v58
	global_store_dword v[92:93], v56, off offset:512
	v_pk_mul_f32 v[56:57], v[52:53], v[2:3] op_sel_hi:[1,0]
	v_pk_mul_f32 v[58:59], v[54:55], v[2:3] op_sel_hi:[1,0]
	global_load_dwordx4 v[52:55], v[0:1], off offset:3072
	s_waitcnt vmcnt(0)
	v_pk_mul_f32 v[52:53], v[52:53], v[56:57]
	v_pk_mul_f32 v[54:55], v[54:55], v[58:59]
	v_mul_f32_e32 v53, 0x41fe0000, v53
	v_mul_f32_e32 v52, 0x41fe0000, v52
	v_med3_f32 v53, v53, s18, v224
	v_mul_f32_e32 v54, 0x41fe0000, v54
	v_mul_f32_e32 v55, 0x41fe0000, v55
	v_med3_f32 v52, v52, s18, v224
	v_rndne_f32_e32 v53, v53
	v_med3_f32 v54, v54, s18, v224
	v_med3_f32 v55, v55, s18, v224
	v_rndne_f32_e32 v52, v52
	v_cvt_i32_f32_e32 v53, v53
	v_rndne_f32_e32 v54, v54
	v_rndne_f32_e32 v55, v55
	v_cvt_i32_f32_e32 v52, v52
	v_cvt_i32_f32_sdwa v54, v54 dst_sel:WORD_1 dst_unused:UNUSED_PAD src0_sel:DWORD
	v_cvt_i32_f32_e32 v55, v55
	v_lshlrev_b32_e32 v53, 8, v53
	v_and_b32_e32 v53, 0xff00, v53
	v_and_b32_e32 v54, 0xff0000, v54
	v_perm_b32 v52, v55, v52, s19
	v_or3_b32 v52, v52, v53, v54
	global_store_dword v[92:93], v52, off offset:768
	v_pk_mul_f32 v[52:53], v[48:49], v[2:3] op_sel_hi:[1,0]
	v_pk_mul_f32 v[54:55], v[50:51], v[2:3] op_sel_hi:[1,0]
	global_load_dwordx4 v[48:51], v[68:69], off
	s_waitcnt vmcnt(0)
	v_pk_mul_f32 v[48:49], v[48:49], v[52:53]
	v_pk_mul_f32 v[50:51], v[50:51], v[54:55]
	v_mul_f32_e32 v49, 0x41fe0000, v49
	v_mul_f32_e32 v48, 0x41fe0000, v48
	v_med3_f32 v49, v49, s18, v224
	v_mul_f32_e32 v50, 0x41fe0000, v50
	v_mul_f32_e32 v51, 0x41fe0000, v51
	v_med3_f32 v48, v48, s18, v224
	v_rndne_f32_e32 v49, v49
	v_med3_f32 v50, v50, s18, v224
	v_med3_f32 v51, v51, s18, v224
	v_rndne_f32_e32 v48, v48
	v_cvt_i32_f32_e32 v49, v49
	v_rndne_f32_e32 v50, v50
	v_rndne_f32_e32 v51, v51
	v_cvt_i32_f32_e32 v48, v48
	v_cvt_i32_f32_sdwa v50, v50 dst_sel:WORD_1 dst_unused:UNUSED_PAD src0_sel:DWORD
	v_cvt_i32_f32_e32 v51, v51
	v_lshlrev_b32_e32 v49, 8, v49
	v_and_b32_e32 v49, 0xff00, v49
	v_and_b32_e32 v50, 0xff0000, v50
	v_perm_b32 v48, v51, v48, s19
	v_or3_b32 v48, v48, v49, v50
	global_store_dword v[92:93], v48, off offset:1024
	v_pk_mul_f32 v[48:49], v[44:45], v[2:3] op_sel_hi:[1,0]
	v_pk_mul_f32 v[50:51], v[46:47], v[2:3] op_sel_hi:[1,0]
	global_load_dwordx4 v[44:47], v[70:71], off
	s_waitcnt vmcnt(0)
	v_pk_mul_f32 v[44:45], v[48:49], v[44:45]
	v_pk_mul_f32 v[46:47], v[50:51], v[46:47]
	v_mul_f32_e32 v45, 0x41fe0000, v45
	v_mul_f32_e32 v44, 0x41fe0000, v44
	v_med3_f32 v45, v45, s18, v224
	v_mul_f32_e32 v46, 0x41fe0000, v46
	v_mul_f32_e32 v47, 0x41fe0000, v47
	v_med3_f32 v44, v44, s18, v224
	v_rndne_f32_e32 v45, v45
	v_med3_f32 v46, v46, s18, v224
	v_med3_f32 v47, v47, s18, v224
	v_rndne_f32_e32 v44, v44
	v_cvt_i32_f32_e32 v45, v45
	v_rndne_f32_e32 v46, v46
	v_rndne_f32_e32 v47, v47
	v_cvt_i32_f32_e32 v44, v44
	v_cvt_i32_f32_sdwa v46, v46 dst_sel:WORD_1 dst_unused:UNUSED_PAD src0_sel:DWORD
	v_cvt_i32_f32_e32 v47, v47
	v_lshlrev_b32_e32 v45, 8, v45
	v_and_b32_e32 v45, 0xff00, v45
	v_and_b32_e32 v46, 0xff0000, v46
	v_perm_b32 v44, v47, v44, s19
	v_or3_b32 v44, v44, v45, v46
	global_store_dword v[92:93], v44, off offset:1280
	v_pk_mul_f32 v[44:45], v[40:41], v[2:3] op_sel_hi:[1,0]
	v_pk_mul_f32 v[46:47], v[42:43], v[2:3] op_sel_hi:[1,0]
	global_load_dwordx4 v[40:43], v[72:73], off
	s_waitcnt vmcnt(0)
; __device__ __forceinline__ unsigned cvt_pk_bf16(float lo, float hi) { unsigned r; asm volatile("v_cvt_pk_bf16_f32 %0, %1, %2" : "=v"(r) : "v"(lo), "v"(hi)); return r; }
; __device__ __forceinline__ unsigned pk4_i8(float a, float b, float c, float d, float qs) {
;     const int q0 = (int)__builtin_rintf(fminf(fmaxf(a * qs, -127.f), 127.f)), q1 = (int)__builtin_rintf(fminf(fmaxf(b * qs, -127.f), 127.f));
;     const int q2 = (int)__builtin_rintf(fminf(fmaxf(c * qs, -127.f), 127.f)), q3 = (int)__builtin_rintf(fminf(fmaxf(d * qs, -127.f), 127.f));
;     return ((unsigned)q0 & 0xffu) | (((unsigned)q1 & 0xffu) << 8) | (((unsigned)q2 & 0xffu) << 16) | ((unsigned)q3 << 24);
; }
; __device__ __forceinline__ void rms_row_to_bf16(const float* xrow, const float* g, bf16_t* orow, int lane, unsigned char* o8row = nullptr) {
;     ...
;     for (int j = 0; j < 16; ++j) { const f32x4 gg = gr[64 * j]; const f32x4 y = v[j] * rstd * gg;
;         if (orow) { u32x2 w; w.x = cvt_pk_bf16(y.x, y.y); w.y = cvt_pk_bf16(y.z, y.w); o8[64 * j] = w; }
;         if (o8row) ((unsigned*)o8row)[lane + 64 * j] = pk4_i8(y.x, y.y, y.z, y.w, XN_QS); }
	v_pk_mul_f32 v[40:41], v[44:45], v[40:41]
	v_pk_mul_f32 v[42:43], v[46:47], v[42:43]
	v_mul_f32_e32 v41, 0x41fe0000, v41
	v_mul_f32_e32 v40, 0x41fe0000, v40
	v_med3_f32 v41, v41, s18, v224
	v_mul_f32_e32 v42, 0x41fe0000, v42
	v_mul_f32_e32 v43, 0x41fe0000, v43
	v_med3_f32 v40, v40, s18, v224
	v_rndne_f32_e32 v41, v41
	v_med3_f32 v42, v42, s18, v224
	v_med3_f32 v43, v43, s18, v224
	v_rndne_f32_e32 v40, v40
	v_cvt_i32_f32_e32 v41, v41
	v_rndne_f32_e32 v42, v42
	v_rndne_f32_e32 v43, v43
	v_cvt_i32_f32_e32 v40, v40
	v_cvt_i32_f32_sdwa v42, v42 dst_sel:WORD_1 dst_unused:UNUSED_PAD src0_sel:DWORD
	v_cvt_i32_f32_e32 v43, v43
	v_lshlrev_b32_e32 v41, 8, v41
	v_and_b32_e32 v41, 0xff00, v41
	v_and_b32_e32 v42, 0xff0000, v42
	v_perm_b32 v40, v43, v40, s19
	v_or3_b32 v40, v40, v41, v42
	global_store_dword v[92:93], v40, off offset:1536
	v_pk_mul_f32 v[40:41], v[36:37], v[2:3] op_sel_hi:[1,0]
	v_pk_mul_f32 v[42:43], v[38:39], v[2:3] op_sel_hi:[1,0]
	global_load_dwordx4 v[36:39], v[74:75], off
	s_waitcnt vmcnt(0)
	v_pk_mul_f32 v[36:37], v[40:41], v[36:37]
	v_pk_mul_f32 v[38:39], v[42:43], v[38:39]
	v_mul_f32_e32 v37, 0x41fe0000, v37
	v_mul_f32_e32 v36, 0x41fe0000, v36
	v_med3_f32 v37, v37, s18, v224
	v_mul_f32_e32 v38, 0x41fe0000, v38
	v_mul_f32_e32 v39, 0x41fe0000, v39
	v_med3_f32 v36, v36, s18, v224
	v_rndne_f32_e32 v37, v37
	v_med3_f32 v38, v38, s18, v224
	v_med3_f32 v39, v39, s18, v224
	v_rndne_f32_e32 v36, v36
	v_cvt_i32_f32_e32 v37, v37
	v_rndne_f32_e32 v38, v38
	v_rndne_f32_e32 v39, v39
	v_cvt_i32_f32_e32 v36, v36
	v_cvt_i32_f32_sdwa v38, v38 dst_sel:WORD_1 dst_unused:UNUSED_PAD src0_sel:DWORD
	v_cvt_i32_f32_e32 v39, v39
	v_lshlrev_b32_e32 v37, 8, v37
	v_and_b32_e32 v37, 0xff00, v37
	v_and_b32_e32 v38, 0xff0000, v38
	v_perm_b32 v36, v39, v36, s19
	v_or3_b32 v36, v36, v37, v38
	global_store_dword v[92:93], v36, off offset:1792
	v_pk_mul_f32 v[36:37], v[32:33], v[2:3] op_sel_hi:[1,0]
	v_pk_mul_f32 v[38:39], v[34:35], v[2:3] op_sel_hi:[1,0]
	global_load_dwordx4 v[32:35], v[76:77], off
	s_waitcnt vmcnt(0)
	v_pk_mul_f32 v[32:33], v[36:37], v[32:33]
	v_pk_mul_f32 v[34:35], v[38:39], v[34:35]
	v_mul_f32_e32 v33, 0x41fe0000, v33
	v_mul_f32_e32 v32, 0x41fe0000, v32
	v_med3_f32 v33, v33, s18, v224
	v_mul_f32_e32 v34, 0x41fe0000, v34
	v_mul_f32_e32 v35, 0x41fe0000, v35
	v_med3_f32 v32, v32, s18, v224
	v_rndne_f32_e32 v33, v33
	v_med3_f32 v34, v34, s18, v224
	v_med3_f32 v35, v35, s18, v224
	v_rndne_f32_e32 v32, v32
	v_cvt_i32_f32_e32 v33, v33
	v_rndne_f32_e32 v34, v34
	v_rndne_f32_e32 v35, v35
	v_cvt_i32_f32_e32 v32, v32
	v_cvt_i32_f32_sdwa v34, v34 dst_sel:WORD_1 dst_unused:UNUSED_PAD src0_sel:DWORD
	v_cvt_i32_f32_e32 v35, v35
	v_lshlrev_b32_e32 v33, 8, v33
	v_and_b32_e32 v33, 0xff00, v33
	v_and_b32_e32 v34, 0xff0000, v34
	v_perm_b32 v32, v35, v32, s19
	v_or3_b32 v32, v32, v33, v34
	global_store_dword v[92:93], v32, off offset:2048
	v_pk_mul_f32 v[32:33], v[28:29], v[2:3] op_sel_hi:[1,0]
	v_pk_mul_f32 v[34:35], v[30:31], v[2:3] op_sel_hi:[1,0]
	global_load_dwordx4 v[28:31], v[78:79], off
	s_waitcnt vmcnt(0)
	v_pk_mul_f32 v[28:29], v[32:33], v[28:29]
	v_pk_mul_f32 v[30:31], v[34:35], v[30:31]
	v_mul_f32_e32 v29, 0x41fe0000, v29
	v_mul_f32_e32 v28, 0x41fe0000, v28
	v_med3_f32 v29, v29, s18, v224
	v_mul_f32_e32 v30, 0x41fe0000, v30
	v_mul_f32_e32 v31, 0x41fe0000, v31
	v_med3_f32 v28, v28, s18, v224
	v_rndne_f32_e32 v29, v29
	v_med3_f32 v30, v30, s18, v224
	v_med3_f32 v31, v31, s18, v224
	v_rndne_f32_e32 v28, v28
	v_cvt_i32_f32_e32 v29, v29
	v_rndne_f32_e32 v30, v30
	v_rndne_f32_e32 v31, v31
	v_cvt_i32_f32_e32 v28, v28
	v_cvt_i32_f32_sdwa v30, v30 dst_sel:WORD_1 dst_unused:UNUSED_PAD src0_sel:DWORD
	v_cvt_i32_f32_e32 v31, v31
	v_lshlrev_b32_e32 v29, 8, v29
	v_and_b32_e32 v29, 0xff00, v29
	v_and_b32_e32 v30, 0xff0000, v30
	v_perm_b32 v28, v31, v28, s19
	v_or3_b32 v28, v28, v29, v30
	global_store_dword v[92:93], v28, off offset:2304
	global_load_dwordx4 v[28:31], v[80:81], off
	s_waitcnt vmcnt(0)
	v_pk_mul_f32 v[24:25], v[24:25], v[28:29]
	v_pk_mul_f32 v[26:27], v[26:27], v[30:31]
	v_mul_f32_e32 v25, 0x41fe0000, v25
	v_mul_f32_e32 v24, 0x41fe0000, v24
	v_med3_f32 v25, v25, s18, v224
	v_mul_f32_e32 v26, 0x41fe0000, v26
	v_mul_f32_e32 v27, 0x41fe0000, v27
	v_med3_f32 v24, v24, s18, v224
	v_rndne_f32_e32 v25, v25
	v_med3_f32 v26, v26, s18, v224
	v_med3_f32 v27, v27, s18, v224
	v_rndne_f32_e32 v24, v24
	v_cvt_i32_f32_e32 v25, v25
	v_rndne_f32_e32 v26, v26
	v_rndne_f32_e32 v27, v27
	v_cvt_i32_f32_e32 v24, v24
	v_cvt_i32_f32_sdwa v26, v26 dst_sel:WORD_1 dst_unused:UNUSED_PAD src0_sel:DWORD
	v_cvt_i32_f32_e32 v27, v27
	v_lshlrev_b32_e32 v25, 8, v25
	v_and_b32_e32 v25, 0xff00, v25
	v_and_b32_e32 v26, 0xff0000, v26
	v_perm_b32 v24, v27, v24, s19
	v_or3_b32 v24, v24, v25, v26
	global_store_dword v[92:93], v24, off offset:2560
	v_pk_mul_f32 v[24:25], v[12:13], v[2:3] op_sel_hi:[1,0]
	v_pk_mul_f32 v[26:27], v[14:15], v[2:3] op_sel_hi:[1,0]
	global_load_dwordx4 v[12:15], v[82:83], off
	s_waitcnt vmcnt(0)
; __device__ __forceinline__ unsigned cvt_pk_bf16(float lo, float hi) { unsigned r; asm volatile("v_cvt_pk_bf16_f32 %0, %1, %2" : "=v"(r) : "v"(lo), "v"(hi)); return r; }
; __device__ __forceinline__ unsigned pk4_i8(float a, float b, float c, float d, float qs) {
;     const int q0 = (int)__builtin_rintf(fminf(fmaxf(a * qs, -127.f), 127.f)), q1 = (int)__builtin_rintf(fminf(fmaxf(b * qs, -127.f), 127.f));
;     const int q2 = (int)__builtin_rintf(fminf(fmaxf(c * qs, -127.f), 127.f)), q3 = (int)__builtin_rintf(fminf(fmaxf(d * qs, -127.f), 127.f));
;     return ((unsigned)q0 & 0xffu) | (((unsigned)q1 & 0xffu) << 8) | (((unsigned)q2 & 0xffu) << 16) | ((unsigned)q3 << 24);
; }
; __device__ __forceinline__ void rms_row_to_bf16(const float* xrow, const float* g, bf16_t* orow, int lane, unsigned char* o8row = nullptr) {
;     ...
;     for (int j = 0; j < 16; ++j) { const f32x4 gg = gr[64 * j]; const f32x4 y = v[j] * rstd * gg;
;         if (orow) { u32x2 w; w.x = cvt_pk_bf16(y.x, y.y); w.y = cvt_pk_bf16(y.z, y.w); o8[64 * j] = w; }
;         if (o8row) ((unsigned*)o8row)[lane + 64 * j] = pk4_i8(y.x, y.y, y.z, y.w, XN_QS); }
	v_pk_mul_f32 v[12:13], v[24:25], v[12:13]
	v_pk_mul_f32 v[14:15], v[26:27], v[14:15]
	v_mul_f32_e32 v13, 0x41fe0000, v13
	v_mul_f32_e32 v12, 0x41fe0000, v12
	v_med3_f32 v13, v13, s18, v224
	v_mul_f32_e32 v14, 0x41fe0000, v14
	v_mul_f32_e32 v15, 0x41fe0000, v15
	v_med3_f32 v12, v12, s18, v224
	v_rndne_f32_e32 v13, v13
	v_med3_f32 v14, v14, s18, v224
	v_med3_f32 v15, v15, s18, v224
	v_rndne_f32_e32 v12, v12
	v_cvt_i32_f32_e32 v13, v13
	v_rndne_f32_e32 v14, v14
	v_rndne_f32_e32 v15, v15
	v_cvt_i32_f32_e32 v12, v12
	v_cvt_i32_f32_sdwa v14, v14 dst_sel:WORD_1 dst_unused:UNUSED_PAD src0_sel:DWORD
	v_cvt_i32_f32_e32 v15, v15
	v_lshlrev_b32_e32 v13, 8, v13
	v_and_b32_e32 v13, 0xff00, v13
	v_and_b32_e32 v14, 0xff0000, v14
	v_perm_b32 v12, v15, v12, s19
	v_or3_b32 v12, v12, v13, v14
	global_store_dword v[92:93], v12, off offset:2816
	global_load_dwordx4 v[12:15], v[84:85], off
	s_waitcnt vmcnt(0)
	v_pk_mul_f32 v[12:13], v[20:21], v[12:13]
	v_pk_mul_f32 v[14:15], v[22:23], v[14:15]
	v_mul_f32_e32 v13, 0x41fe0000, v13
	v_mul_f32_e32 v12, 0x41fe0000, v12
	v_med3_f32 v13, v13, s18, v224
	v_mul_f32_e32 v14, 0x41fe0000, v14
	v_mul_f32_e32 v15, 0x41fe0000, v15
	v_med3_f32 v12, v12, s18, v224
	v_rndne_f32_e32 v13, v13
	v_med3_f32 v14, v14, s18, v224
	v_med3_f32 v15, v15, s18, v224
	v_rndne_f32_e32 v12, v12
	v_cvt_i32_f32_e32 v13, v13
	v_rndne_f32_e32 v14, v14
	v_rndne_f32_e32 v15, v15
	v_cvt_i32_f32_e32 v12, v12
	v_cvt_i32_f32_sdwa v14, v14 dst_sel:WORD_1 dst_unused:UNUSED_PAD src0_sel:DWORD
	v_cvt_i32_f32_e32 v15, v15
	v_lshlrev_b32_e32 v13, 8, v13
	v_and_b32_e32 v13, 0xff00, v13
	v_and_b32_e32 v14, 0xff0000, v14
	v_perm_b32 v12, v15, v12, s19
	v_or3_b32 v12, v12, v13, v14
	global_store_dword v[92:93], v12, off offset:3072
	global_load_dwordx4 v[12:15], v[86:87], off
	s_waitcnt vmcnt(0)
	v_pk_mul_f32 v[12:13], v[16:17], v[12:13]
	v_pk_mul_f32 v[14:15], v[18:19], v[14:15]
	v_mul_f32_e32 v13, 0x41fe0000, v13
	v_mul_f32_e32 v12, 0x41fe0000, v12
	v_med3_f32 v13, v13, s18, v224
	v_mul_f32_e32 v14, 0x41fe0000, v14
	v_mul_f32_e32 v15, 0x41fe0000, v15
	v_med3_f32 v12, v12, s18, v224
	v_rndne_f32_e32 v13, v13
	v_med3_f32 v14, v14, s18, v224
	v_med3_f32 v15, v15, s18, v224
	v_rndne_f32_e32 v12, v12
	v_cvt_i32_f32_e32 v13, v13
	v_rndne_f32_e32 v14, v14
	v_rndne_f32_e32 v15, v15
	v_cvt_i32_f32_e32 v12, v12
	v_cvt_i32_f32_sdwa v14, v14 dst_sel:WORD_1 dst_unused:UNUSED_PAD src0_sel:DWORD
	v_cvt_i32_f32_e32 v15, v15
	v_lshlrev_b32_e32 v13, 8, v13
	v_and_b32_e32 v13, 0xff00, v13
	v_and_b32_e32 v14, 0xff0000, v14
	v_perm_b32 v12, v15, v12, s19
	v_or3_b32 v12, v12, v13, v14
	global_store_dword v[92:93], v12, off offset:3328
	v_pk_mul_f32 v[12:13], v[8:9], v[2:3] op_sel_hi:[1,0]
	v_pk_mul_f32 v[14:15], v[10:11], v[2:3] op_sel_hi:[1,0]
	global_load_dwordx4 v[8:11], v[88:89], off
	s_waitcnt vmcnt(0)
	v_pk_mul_f32 v[8:9], v[12:13], v[8:9]
	v_pk_mul_f32 v[10:11], v[14:15], v[10:11]
	v_mul_f32_e32 v9, 0x41fe0000, v9
	v_mul_f32_e32 v8, 0x41fe0000, v8
	v_med3_f32 v9, v9, s18, v224
	v_mul_f32_e32 v10, 0x41fe0000, v10
	v_mul_f32_e32 v11, 0x41fe0000, v11
	v_med3_f32 v8, v8, s18, v224
	v_rndne_f32_e32 v9, v9
	v_med3_f32 v10, v10, s18, v224
	v_med3_f32 v11, v11, s18, v224
	v_rndne_f32_e32 v8, v8
	v_cvt_i32_f32_e32 v9, v9
	v_rndne_f32_e32 v10, v10
	v_rndne_f32_e32 v11, v11
	v_cvt_i32_f32_e32 v8, v8
	v_cvt_i32_f32_sdwa v10, v10 dst_sel:WORD_1 dst_unused:UNUSED_PAD src0_sel:DWORD
	v_cvt_i32_f32_e32 v11, v11
	v_lshlrev_b32_e32 v9, 8, v9
	v_and_b32_e32 v9, 0xff00, v9
	v_and_b32_e32 v10, 0xff0000, v10
	v_perm_b32 v8, v11, v8, s19
	v_or3_b32 v8, v8, v9, v10
	global_store_dword v[92:93], v8, off offset:3584
	v_pk_mul_f32 v[8:9], v[4:5], v[2:3] op_sel_hi:[1,0]
	v_pk_mul_f32 v[10:11], v[6:7], v[2:3] op_sel_hi:[1,0]
	global_load_dwordx4 v[4:7], v[90:91], off
	s_waitcnt vmcnt(0)
	v_pk_mul_f32 v[4:5], v[8:9], v[4:5]
	v_pk_mul_f32 v[6:7], v[10:11], v[6:7]
	v_mul_f32_e32 v2, 0x41fe0000, v4
	v_mul_f32_e32 v4, 0x41fe0000, v5
	v_med3_f32 v4, v4, s18, v224
	v_mul_f32_e32 v5, 0x41fe0000, v6
	v_mul_f32_e32 v6, 0x41fe0000, v7
	v_med3_f32 v2, v2, s18, v224
	v_rndne_f32_e32 v4, v4
	v_med3_f32 v5, v5, s18, v224
	v_med3_f32 v6, v6, s18, v224
	v_rndne_f32_e32 v2, v2
	v_cvt_i32_f32_e32 v4, v4
	v_rndne_f32_e32 v5, v5
	v_rndne_f32_e32 v6, v6
	v_cvt_i32_f32_e32 v2, v2
	v_cvt_i32_f32_sdwa v5, v5 dst_sel:WORD_1 dst_unused:UNUSED_PAD src0_sel:DWORD
	v_cvt_i32_f32_e32 v6, v6
	v_lshlrev_b32_e32 v4, 8, v4
	v_and_b32_e32 v4, 0xff00, v4
	v_and_b32_e32 v5, 0xff0000, v5
	v_perm_b32 v2, v6, v2, s19
	v_or3_b32 v2, v2, v4, v5
	global_store_dword v[92:93], v2, off offset:3840
	v_lshl_add_u64 v[92:93], v[92:93], 0, s[28:29]
	s_cbranch_scc1 .LBB0_921
